# PEER up: list entries read as 16-bit halves (ds_read_u16_d16_hi -> h directly, ds_read_u16 -> expert id): per-row VALU 3 -> 1 (no shift for h, one lshl_add for the address)
# speedup vs baseline: 1.0253x; 1.0079x over previous
; DI void up_issue(u32x4 (&W)[16], u32 (&pj)[16], const u32* pl, const unsigned char* wbase, int grp) {
; #pragma unroll
;   for (int j = 0; j < 16; ++j) {
;     pj[j] = pl[8 * j + grp];
;     W[j] = *(const u32x4*)(wbase + (size_t)(pj[j] >> 16) * 1024);
;   }
; }
; DI void peer_up_phase(const Params& p, unsigned char* smem, int layer, u32* ctr) {
;     ...
;       if (item >= 256) break;
;       const int t0 = item * 64 + 16 * w;
;       const unsigned char* wbase = wu + slice * 128 + c * 16;
;       {
;         const u32* src = hgp + (size_t)t0 * 128;
; #pragma unroll
;         for (int i = 0; i < 32; ++i) pl[i * 64 + lane] = src[i * 64 + lane];
;       }
;       float* ybase = yb + (size_t)t0 * 1024 + slice * 128;
;       u32x4 WA[16], WB[16];
;       u32 pA[16], pB[16];
;       up_issue(WA, pA, pl, wbase, grp);
.LBB0_824:
	v_cmp_lt_i32_e32 vcc, s48, v4
	s_mov_b64 s[28:29], -1
	s_cbranch_vccnz .LBB0_815
	s_waitcnt vmcnt(3)
	v_lshl_add_u32 v68, v4, 6, v3
	v_ashrrev_i32_e32 v69, 31, v68
	v_lshlrev_b64 v[4:5], 9, v[68:69]
	v_lshl_add_u64 v[4:5], s[38:39], 0, v[4:5]
	v_mov_b32_e32 v139, v133
	v_lshl_add_u64 v[6:7], v[4:5], 0, v[138:139]
	global_load_dword v38, v[6:7], off
	global_load_dword v39, v[6:7], off offset:256
	v_mov_b32_e32 v141, v133
	v_mov_b32_e32 v143, v133
	v_mov_b32_e32 v145, v133
	v_mov_b32_e32 v147, v133
	v_mov_b32_e32 v149, v133
	v_mov_b32_e32 v151, v133
	v_mov_b32_e32 v153, v133
	v_mov_b32_e32 v155, v133
	v_mov_b32_e32 v157, v133
	v_mov_b32_e32 v159, v133
	v_mov_b32_e32 v163, v133
	v_mov_b32_e32 v165, v133
	v_mov_b32_e32 v167, v133
	v_mov_b32_e32 v169, v133
	v_mov_b32_e32 v171, v133
	v_mov_b32_e32 v173, v133
	v_lshl_add_u64 v[8:9], v[4:5], 0, v[140:141]
	v_lshl_add_u64 v[10:11], v[4:5], 0, v[142:143]
	v_lshl_add_u64 v[12:13], v[4:5], 0, v[144:145]
	v_lshl_add_u64 v[14:15], v[4:5], 0, v[146:147]
	v_lshl_add_u64 v[16:17], v[4:5], 0, v[148:149]
	v_lshl_add_u64 v[18:19], v[4:5], 0, v[150:151]
	v_lshl_add_u64 v[20:21], v[4:5], 0, v[152:153]
	v_lshl_add_u64 v[22:23], v[4:5], 0, v[154:155]
	v_lshl_add_u64 v[24:25], v[4:5], 0, v[156:157]
	v_lshl_add_u64 v[26:27], v[4:5], 0, v[158:159]
	v_lshl_add_u64 v[28:29], v[4:5], 0, v[162:163]
	v_lshl_add_u64 v[30:31], v[4:5], 0, v[164:165]
	v_lshl_add_u64 v[32:33], v[4:5], 0, v[166:167]
	v_lshl_add_u64 v[34:35], v[4:5], 0, v[168:169]
	v_lshl_add_u64 v[36:37], v[4:5], 0, v[170:171]
	v_lshl_add_u64 v[4:5], v[4:5], 0, v[172:173]
	global_load_dword v70, v[6:7], off offset:512
	global_load_dword v71, v[6:7], off offset:768
	global_load_dword v72, v[6:7], off offset:1024
	global_load_dword v73, v[6:7], off offset:1280
	global_load_dword v74, v[6:7], off offset:1536
	global_load_dword v75, v[6:7], off offset:1792
	global_load_dword v76, v[6:7], off offset:2048
	global_load_dword v77, v[6:7], off offset:2304
	global_load_dword v78, v[6:7], off offset:2560
	global_load_dword v79, v[6:7], off offset:2816
	global_load_dword v80, v[6:7], off offset:3072
	global_load_dword v81, v[6:7], off offset:3328
	global_load_dword v82, v[6:7], off offset:3584
	global_load_dword v83, v[6:7], off offset:3840
	global_load_dword v84, v[8:9], off
	global_load_dword v85, v[10:11], off
	global_load_dword v86, v[12:13], off
	global_load_dword v87, v[14:15], off
	global_load_dword v88, v[16:17], off
	global_load_dword v89, v[18:19], off
	global_load_dword v90, v[20:21], off
	global_load_dword v91, v[22:23], off
	global_load_dword v92, v[24:25], off
	global_load_dword v93, v[26:27], off
	global_load_dword v94, v[28:29], off
	global_load_dword v95, v[30:31], off
	global_load_dword v96, v[32:33], off
	global_load_dword v97, v[34:35], off
	global_load_dword v98, v[36:37], off
	global_load_dword v99, v[4:5], off
	v_cmp_lt_i32_e32 vcc, v223, v218
	v_lshlrev_b64 v[68:69], 12, v[68:69]
	s_mov_b32 s44, 0
	v_lshl_add_u64 v[188:189], v[176:177], 0, v[68:69]
	v_mov_b32_e32 v145, v214
	s_waitcnt vmcnt(30)
	ds_write2st64_b32 v213, v38, v39 offset0:1 offset1:2
	ds_read2_b32 v[178:179], v212 offset0:64 offset1:72
	ds_read2_b32 v[180:181], v212 offset0:80 offset1:88
	ds_read2_b32 v[182:183], v212 offset0:96 offset1:104
	ds_read2_b32 v[184:185], v212 offset0:112 offset1:120
	ds_read2_b32 v[186:187], v212 offset0:128 offset1:136
	s_waitcnt lgkmcnt(4)
	v_lshlrev_b32_sdwa v132, v215, v178 dst_sel:DWORD dst_unused:UNUSED_PAD src0_sel:DWORD src1_sel:WORD_1
	v_add_u32_e32 v4, v250, v132
	v_lshlrev_b32_sdwa v132, v215, v179 dst_sel:DWORD dst_unused:UNUSED_PAD src0_sel:DWORD src1_sel:WORD_1
	v_add_u32_e32 v8, v250, v132
	s_waitcnt lgkmcnt(3)
	v_lshlrev_b32_sdwa v132, v215, v180 dst_sel:DWORD dst_unused:UNUSED_PAD src0_sel:DWORD src1_sel:WORD_1
	v_add_u32_e32 v12, v250, v132
	v_lshlrev_b32_sdwa v132, v215, v181 dst_sel:DWORD dst_unused:UNUSED_PAD src0_sel:DWORD src1_sel:WORD_1
	v_add_u32_e32 v16, v250, v132
	s_waitcnt lgkmcnt(2)
	v_lshlrev_b32_sdwa v132, v215, v182 dst_sel:DWORD dst_unused:UNUSED_PAD src0_sel:DWORD src1_sel:WORD_1
	v_add_u32_e32 v20, v250, v132
	v_lshlrev_b32_sdwa v132, v215, v183 dst_sel:DWORD dst_unused:UNUSED_PAD src0_sel:DWORD src1_sel:WORD_1
	v_add_u32_e32 v24, v250, v132
	s_waitcnt lgkmcnt(1)
	v_lshlrev_b32_sdwa v132, v215, v184 dst_sel:DWORD dst_unused:UNUSED_PAD src0_sel:DWORD src1_sel:WORD_1
	v_add_u32_e32 v28, v250, v132
	v_lshlrev_b32_sdwa v132, v215, v185 dst_sel:DWORD dst_unused:UNUSED_PAD src0_sel:DWORD src1_sel:WORD_1
	v_add_u32_e32 v32, v250, v132
	global_load_dwordx4 v[4:7], v4, s[98:99]
	s_nop 0
	global_load_dwordx4 v[8:11], v8, s[98:99]
	s_nop 0
	global_load_dwordx4 v[12:15], v12, s[98:99]
	s_nop 0
	global_load_dwordx4 v[16:19], v16, s[98:99]
	s_nop 0
	global_load_dwordx4 v[20:23], v20, s[98:99]
	s_nop 0
	global_load_dwordx4 v[24:27], v24, s[98:99]
	s_nop 0
	global_load_dwordx4 v[28:31], v28, s[98:99]
	s_nop 0
	global_load_dwordx4 v[32:35], v32, s[98:99]
	ds_read2_b32 v[190:191], v212 offset0:144 offset1:152
	s_waitcnt lgkmcnt(1)
	v_lshlrev_b32_sdwa v132, v215, v186 dst_sel:DWORD dst_unused:UNUSED_PAD src0_sel:DWORD src1_sel:WORD_1
	v_add_u32_e32 v36, v250, v132
	v_lshlrev_b32_sdwa v132, v215, v187 dst_sel:DWORD dst_unused:UNUSED_PAD src0_sel:DWORD src1_sel:WORD_1
	v_add_u32_e32 v40, v250, v132
	s_waitcnt lgkmcnt(0)
	v_lshlrev_b32_sdwa v132, v215, v190 dst_sel:DWORD dst_unused:UNUSED_PAD src0_sel:DWORD src1_sel:WORD_1
	global_load_dwordx4 v[36:39], v36, s[98:99]
	s_nop 0
	global_load_dwordx4 v[40:43], v40, s[98:99]
	v_add_u32_e32 v44, v250, v132
	ds_read2_b32 v[192:193], v212 offset0:160 offset1:168
	v_lshlrev_b32_sdwa v132, v215, v191 dst_sel:DWORD dst_unused:UNUSED_PAD src0_sel:DWORD src1_sel:WORD_1
	v_add_u32_e32 v48, v250, v132
	global_load_dwordx4 v[44:47], v44, s[98:99]
	s_nop 0
	global_load_dwordx4 v[48:51], v48, s[98:99]
	ds_read2_b32 v[194:195], v212 offset0:176 offset1:184
	s_waitcnt lgkmcnt(1)
; DI void up_math(const u32x4 (&W)[16], const u32 (&pj)[16], float* __restrict__ yrow, int lane) {
;     ...
;   for (int j = 0; j < 16; ++j) {
;     const float h = __uint_as_float(pj[j] << 16);
;     const f2 hh = {h, h};
; #pragma unroll
;     for (int d = 0; d < 4; ++d) {
;       f2 lo = __builtin_amdgcn_cvt_pk_f32_fp8((int)W[j][d], false);
;       f2 hi = __builtin_amdgcn_cvt_pk_f32_fp8((int)W[j][d], true);
;       y[2 * d] = lo * hh + y[2 * d];
;       y[2 * d + 1] = hi * hh + y[2 * d + 1];
;     }
;   }
; DI void peer_up_phase(const Params& p, unsigned char* smem, int layer, u32* ctr) {
;     ...
;       {
;         const u32* src = hgp + (size_t)t0 * 128;
; #pragma unroll
;         for (int i = 0; i < 32; ++i) pl[i * 64 + lane] = src[i * 64 + lane];
;       }
;       float* ybase = yb + (size_t)t0 * 1024 + slice * 128;
;       u32x4 WA[16], WB[16];
;       u32 pA[16], pB[16];
;       up_issue(WA, pA, pl, wbase, grp);
	v_lshlrev_b32_sdwa v132, v215, v192 dst_sel:DWORD dst_unused:UNUSED_PAD src0_sel:DWORD src1_sel:WORD_1
	v_add_u32_e32 v52, v250, v132
	v_lshlrev_b32_sdwa v132, v215, v193 dst_sel:DWORD dst_unused:UNUSED_PAD src0_sel:DWORD src1_sel:WORD_1
	v_add_u32_e32 v56, v250, v132
	s_waitcnt lgkmcnt(0)
	v_lshlrev_b32_sdwa v132, v215, v194 dst_sel:DWORD dst_unused:UNUSED_PAD src0_sel:DWORD src1_sel:WORD_1
	v_add_u32_e32 v60, v250, v132
	v_lshlrev_b32_sdwa v132, v215, v195 dst_sel:DWORD dst_unused:UNUSED_PAD src0_sel:DWORD src1_sel:WORD_1
	v_add_u32_e32 v64, v250, v132
	global_load_dwordx4 v[52:55], v52, s[98:99]
	s_nop 0
	global_load_dwordx4 v[56:59], v56, s[98:99]
	s_nop 0
	global_load_dwordx4 v[60:63], v60, s[98:99]
	s_nop 0
	global_load_dwordx4 v[64:67], v64, s[98:99]
	s_waitcnt vmcnt(44)
	ds_write2st64_b32 v213, v70, v71 offset0:3 offset1:4
	s_waitcnt vmcnt(42)
	ds_write2st64_b32 v213, v72, v73 offset0:5 offset1:6
	s_waitcnt vmcnt(40)
	ds_write2st64_b32 v213, v74, v75 offset0:7 offset1:8
	s_waitcnt vmcnt(38)
	ds_write2st64_b32 v213, v76, v77 offset0:9 offset1:10
	s_waitcnt vmcnt(36)
	ds_write2st64_b32 v213, v78, v79 offset0:11 offset1:12
	s_waitcnt vmcnt(34)
	ds_write2st64_b32 v213, v80, v81 offset0:13 offset1:14
	s_waitcnt vmcnt(32)
	ds_write2st64_b32 v213, v82, v83 offset0:15 offset1:16
	s_waitcnt vmcnt(30)
	ds_write2st64_b32 v213, v84, v85 offset0:17 offset1:18
	s_waitcnt vmcnt(28)
	ds_write2st64_b32 v213, v86, v87 offset0:19 offset1:20
	s_waitcnt vmcnt(26)
	ds_write2st64_b32 v213, v88, v89 offset0:21 offset1:22
	s_waitcnt vmcnt(24)
	ds_write2st64_b32 v213, v90, v91 offset0:23 offset1:24
	s_waitcnt vmcnt(22)
	ds_write2st64_b32 v213, v92, v93 offset0:25 offset1:26
	s_waitcnt vmcnt(20)
	ds_write2st64_b32 v213, v94, v95 offset0:27 offset1:28
	s_waitcnt vmcnt(18)
	ds_write2st64_b32 v213, v96, v97 offset0:29 offset1:30
	s_waitcnt vmcnt(16)
	ds_write2st64_b32 v213, v98, v99 offset0:31 offset1:32
	v_cndmask_b32_e32 v70, v161, v223, vcc
	v_cmp_lt_i32_e32 vcc, v224, v218
	v_lshlrev_b32_e32 v139, 2, v70
	s_nop 0
	v_cndmask_b32_e32 v70, v161, v224, vcc
	v_cmp_lt_i32_e32 vcc, v222, v218
	v_lshlrev_b32_e32 v141, 2, v70
	s_nop 0
	v_cndmask_b32_e32 v70, v161, v222, vcc
	v_lshlrev_b32_e32 v143, 2, v70
	v_lshlrev_b32_e32 v178, 16, v178
	v_lshlrev_b32_e32 v179, 16, v179
	v_lshlrev_b32_e32 v180, 16, v180
	v_lshlrev_b32_e32 v181, 16, v181
	v_lshlrev_b32_e32 v182, 16, v182
	v_lshlrev_b32_e32 v183, 16, v183
	v_lshlrev_b32_e32 v184, 16, v184
	v_lshlrev_b32_e32 v185, 16, v185
	v_lshlrev_b32_e32 v186, 16, v186
	v_lshlrev_b32_e32 v187, 16, v187
	v_lshlrev_b32_e32 v190, 16, v190
	v_lshlrev_b32_e32 v191, 16, v191
	v_lshlrev_b32_e32 v192, 16, v192
	v_lshlrev_b32_e32 v193, 16, v193
	v_lshlrev_b32_e32 v194, 16, v194
	v_lshlrev_b32_e32 v195, 16, v195
	v_mov_b32_e32 v210, 0
	v_mov_b32_e32 v211, 0
	v_mov_b32_e32 v208, 0
	v_mov_b32_e32 v209, 0
	v_mov_b32_e32 v206, 0
	v_mov_b32_e32 v207, 0
	v_mov_b32_e32 v204, 0
	v_mov_b32_e32 v205, 0
	v_mov_b32_e32 v202, 0
	v_mov_b32_e32 v203, 0
	v_mov_b32_e32 v200, 0
	v_mov_b32_e32 v201, 0
	v_mov_b32_e32 v198, 0
	v_mov_b32_e32 v199, 0
	v_mov_b32_e32 v196, 0
	v_mov_b32_e32 v197, 0
	s_branch .LBB0_827
.LBB0_826:
	s_add_i32 s44, s44, 2
	s_waitcnt vmcnt(16)
	v_cvt_pk_f32_fp8_e32 v[216:217], v128
	v_cvt_pk_f32_fp8_sdwa v[226:227], v128 src0_sel:WORD_1
	v_cvt_pk_f32_fp8_e32 v[228:229], v129
	v_cvt_pk_f32_fp8_sdwa v[128:129], v129 src0_sel:WORD_1
	v_cvt_pk_f32_fp8_e32 v[230:231], v130
	v_cvt_pk_f32_fp8_sdwa v[232:233], v130 src0_sel:WORD_1
	v_cvt_pk_f32_fp8_e32 v[234:235], v131
	v_cvt_pk_f32_fp8_sdwa v[130:131], v131 src0_sel:WORD_1
	v_pk_fma_f32 v[216:217], v[210:211], v[216:217], 0 op_sel_hi:[0,1,0]
	v_pk_fma_f32 v[226:227], v[210:211], v[226:227], 0 op_sel_hi:[0,1,0]
	v_pk_fma_f32 v[228:229], v[210:211], v[228:229], 0 op_sel_hi:[0,1,0]
	v_pk_fma_f32 v[128:129], v[210:211], v[128:129], 0 op_sel_hi:[0,1,0]
	v_pk_fma_f32 v[230:231], v[210:211], v[230:231], 0 op_sel_hi:[0,1,0]
	v_pk_fma_f32 v[232:233], v[210:211], v[232:233], 0 op_sel_hi:[0,1,0]
	v_pk_fma_f32 v[234:235], v[210:211], v[234:235], 0 op_sel_hi:[0,1,0]
	v_pk_fma_f32 v[130:131], v[210:211], v[130:131], 0 op_sel_hi:[0,1,0]
	v_mov_b32_e32 v132, v211
	s_waitcnt vmcnt(15)
	v_cvt_pk_f32_fp8_e32 v[210:211], v124
	v_cvt_pk_f32_fp8_sdwa v[236:237], v124 src0_sel:WORD_1
	v_cvt_pk_f32_fp8_e32 v[238:239], v125
	v_cvt_pk_f32_fp8_sdwa v[124:125], v125 src0_sel:WORD_1
	v_pk_fma_f32 v[210:211], v[132:133], v[210:211], v[216:217] op_sel_hi:[0,1,1]
	v_pk_fma_f32 v[216:217], v[132:133], v[236:237], v[226:227] op_sel_hi:[0,1,1]
	v_pk_fma_f32 v[226:227], v[132:133], v[238:239], v[228:229] op_sel_hi:[0,1,1]
	v_pk_fma_f32 v[124:125], v[132:133], v[124:125], v[128:129] op_sel_hi:[0,1,1]
	v_cvt_pk_f32_fp8_e32 v[128:129], v126
	v_cvt_pk_f32_fp8_sdwa v[228:229], v126 src0_sel:WORD_1
	v_cvt_pk_f32_fp8_e32 v[236:237], v127
	v_cvt_pk_f32_fp8_sdwa v[126:127], v127 src0_sel:WORD_1
	v_pk_fma_f32 v[128:129], v[132:133], v[128:129], v[230:231] op_sel_hi:[0,1,1]
	v_pk_fma_f32 v[228:229], v[132:133], v[228:229], v[232:233] op_sel_hi:[0,1,1]
	v_pk_fma_f32 v[230:231], v[132:133], v[236:237], v[234:235] op_sel_hi:[0,1,1]
	s_waitcnt vmcnt(14)
; DI void up_math(const u32x4 (&W)[16], const u32 (&pj)[16], float* __restrict__ yrow, int lane) {
;     ...
;   for (int j = 0; j < 16; ++j) {
;     const float h = __uint_as_float(pj[j] << 16);
;     const f2 hh = {h, h};
; #pragma unroll
;     for (int d = 0; d < 4; ++d) {
;       f2 lo = __builtin_amdgcn_cvt_pk_f32_fp8((int)W[j][d], false);
;       f2 hi = __builtin_amdgcn_cvt_pk_f32_fp8((int)W[j][d], true);
;       y[2 * d] = lo * hh + y[2 * d];
;       y[2 * d + 1] = hi * hh + y[2 * d + 1];
;     }
;   }
	v_cvt_pk_f32_fp8_e32 v[232:233], v120
	v_cvt_pk_f32_fp8_sdwa v[234:235], v120 src0_sel:WORD_1
	v_cvt_pk_f32_fp8_e32 v[236:237], v121
	v_cvt_pk_f32_fp8_sdwa v[120:121], v121 src0_sel:WORD_1
	v_pk_fma_f32 v[126:127], v[132:133], v[126:127], v[130:131] op_sel_hi:[0,1,1]
	v_pk_fma_f32 v[210:211], v[208:209], v[232:233], v[210:211] op_sel_hi:[0,1,1]
	v_pk_fma_f32 v[216:217], v[208:209], v[234:235], v[216:217] op_sel_hi:[0,1,1]
	v_pk_fma_f32 v[120:121], v[208:209], v[120:121], v[124:125] op_sel_hi:[0,1,1]
	v_cvt_pk_f32_fp8_e32 v[124:125], v122
	v_cvt_pk_f32_fp8_sdwa v[232:233], v122 src0_sel:WORD_1
	v_cvt_pk_f32_fp8_e32 v[234:235], v123
	v_cvt_pk_f32_fp8_sdwa v[122:123], v123 src0_sel:WORD_1
	v_pk_fma_f32 v[226:227], v[208:209], v[236:237], v[226:227] op_sel_hi:[0,1,1]
	v_pk_fma_f32 v[124:125], v[208:209], v[124:125], v[128:129] op_sel_hi:[0,1,1]
	v_pk_fma_f32 v[128:129], v[208:209], v[232:233], v[228:229] op_sel_hi:[0,1,1]
	v_pk_fma_f32 v[228:229], v[208:209], v[234:235], v[230:231] op_sel_hi:[0,1,1]
	v_pk_fma_f32 v[122:123], v[208:209], v[122:123], v[126:127] op_sel_hi:[0,1,1]
	v_mov_b32_e32 v126, v209
	s_waitcnt vmcnt(13)
	v_cvt_pk_f32_fp8_e32 v[130:131], v116
	v_cvt_pk_f32_fp8_sdwa v[208:209], v116 src0_sel:WORD_1
	v_cvt_pk_f32_fp8_e32 v[230:231], v117
	v_cvt_pk_f32_fp8_sdwa v[116:117], v117 src0_sel:WORD_1
	v_pk_fma_f32 v[130:131], v[126:127], v[130:131], v[210:211] op_sel_hi:[0,1,1]
	v_pk_fma_f32 v[208:209], v[126:127], v[208:209], v[216:217] op_sel_hi:[0,1,1]
	v_pk_fma_f32 v[210:211], v[126:127], v[230:231], v[226:227] op_sel_hi:[0,1,1]
	v_pk_fma_f32 v[116:117], v[126:127], v[116:117], v[120:121] op_sel_hi:[0,1,1]
	v_cvt_pk_f32_fp8_e32 v[120:121], v118
	v_cvt_pk_f32_fp8_sdwa v[216:217], v118 src0_sel:WORD_1
	v_cvt_pk_f32_fp8_e32 v[226:227], v119
	v_cvt_pk_f32_fp8_sdwa v[118:119], v119 src0_sel:WORD_1
	v_pk_fma_f32 v[120:121], v[126:127], v[120:121], v[124:125] op_sel_hi:[0,1,1]
	v_pk_fma_f32 v[124:125], v[126:127], v[216:217], v[128:129] op_sel_hi:[0,1,1]
	v_pk_fma_f32 v[128:129], v[126:127], v[226:227], v[228:229] op_sel_hi:[0,1,1]
	v_pk_fma_f32 v[118:119], v[126:127], v[118:119], v[122:123] op_sel_hi:[0,1,1]
	s_waitcnt vmcnt(12)
	v_cvt_pk_f32_fp8_e32 v[126:127], v112
	v_cvt_pk_f32_fp8_sdwa v[216:217], v112 src0_sel:WORD_1
	v_cvt_pk_f32_fp8_e32 v[226:227], v113
	v_cvt_pk_f32_fp8_sdwa v[112:113], v113 src0_sel:WORD_1
	v_pk_fma_f32 v[126:127], v[206:207], v[126:127], v[130:131] op_sel_hi:[0,1,1]
	v_pk_fma_f32 v[130:131], v[206:207], v[216:217], v[208:209] op_sel_hi:[0,1,1]
	v_pk_fma_f32 v[208:209], v[206:207], v[226:227], v[210:211] op_sel_hi:[0,1,1]
	v_pk_fma_f32 v[112:113], v[206:207], v[112:113], v[116:117] op_sel_hi:[0,1,1]
	v_cvt_pk_f32_fp8_e32 v[116:117], v114
	v_cvt_pk_f32_fp8_sdwa v[210:211], v114 src0_sel:WORD_1
	v_cvt_pk_f32_fp8_e32 v[216:217], v115
	v_cvt_pk_f32_fp8_sdwa v[114:115], v115 src0_sel:WORD_1
	v_pk_fma_f32 v[116:117], v[206:207], v[116:117], v[120:121] op_sel_hi:[0,1,1]
	v_pk_fma_f32 v[120:121], v[206:207], v[210:211], v[124:125] op_sel_hi:[0,1,1]
	v_pk_fma_f32 v[124:125], v[206:207], v[216:217], v[128:129] op_sel_hi:[0,1,1]
	v_pk_fma_f32 v[114:115], v[206:207], v[114:115], v[118:119] op_sel_hi:[0,1,1]
	v_mov_b32_e32 v118, v207
	s_waitcnt vmcnt(11)
	v_cvt_pk_f32_fp8_e32 v[122:123], v108
	v_cvt_pk_f32_fp8_sdwa v[128:129], v108 src0_sel:WORD_1
	v_cvt_pk_f32_fp8_e32 v[206:207], v109
	v_cvt_pk_f32_fp8_sdwa v[108:109], v109 src0_sel:WORD_1
	v_pk_fma_f32 v[122:123], v[118:119], v[122:123], v[126:127] op_sel_hi:[0,1,1]
	v_pk_fma_f32 v[126:127], v[118:119], v[128:129], v[130:131] op_sel_hi:[0,1,1]
	v_pk_fma_f32 v[128:129], v[118:119], v[206:207], v[208:209] op_sel_hi:[0,1,1]
	v_pk_fma_f32 v[108:109], v[118:119], v[108:109], v[112:113] op_sel_hi:[0,1,1]
	v_cvt_pk_f32_fp8_e32 v[112:113], v110
	v_cvt_pk_f32_fp8_sdwa v[130:131], v110 src0_sel:WORD_1
	v_cvt_pk_f32_fp8_e32 v[206:207], v111
	v_cvt_pk_f32_fp8_sdwa v[110:111], v111 src0_sel:WORD_1
	v_pk_fma_f32 v[112:113], v[118:119], v[112:113], v[116:117] op_sel_hi:[0,1,1]
	v_pk_fma_f32 v[116:117], v[118:119], v[130:131], v[120:121] op_sel_hi:[0,1,1]
	v_pk_fma_f32 v[120:121], v[118:119], v[206:207], v[124:125] op_sel_hi:[0,1,1]
	v_pk_fma_f32 v[110:111], v[118:119], v[110:111], v[114:115] op_sel_hi:[0,1,1]
	s_waitcnt vmcnt(10)
	v_cvt_pk_f32_fp8_e32 v[118:119], v104
	v_cvt_pk_f32_fp8_sdwa v[124:125], v104 src0_sel:WORD_1
	v_cvt_pk_f32_fp8_e32 v[130:131], v105
	v_cvt_pk_f32_fp8_sdwa v[104:105], v105 src0_sel:WORD_1
	v_pk_fma_f32 v[118:119], v[204:205], v[118:119], v[122:123] op_sel_hi:[0,1,1]
	v_pk_fma_f32 v[122:123], v[204:205], v[124:125], v[126:127] op_sel_hi:[0,1,1]
	v_pk_fma_f32 v[124:125], v[204:205], v[130:131], v[128:129] op_sel_hi:[0,1,1]
	v_pk_fma_f32 v[104:105], v[204:205], v[104:105], v[108:109] op_sel_hi:[0,1,1]
	v_cvt_pk_f32_fp8_e32 v[108:109], v106
	v_cvt_pk_f32_fp8_sdwa v[126:127], v106 src0_sel:WORD_1
	v_cvt_pk_f32_fp8_e32 v[128:129], v107
	v_cvt_pk_f32_fp8_sdwa v[106:107], v107 src0_sel:WORD_1
	v_pk_fma_f32 v[108:109], v[204:205], v[108:109], v[112:113] op_sel_hi:[0,1,1]
	v_pk_fma_f32 v[112:113], v[204:205], v[126:127], v[116:117] op_sel_hi:[0,1,1]
	v_pk_fma_f32 v[116:117], v[204:205], v[128:129], v[120:121] op_sel_hi:[0,1,1]
	v_pk_fma_f32 v[106:107], v[204:205], v[106:107], v[110:111] op_sel_hi:[0,1,1]
	s_waitcnt vmcnt(9)
; DI void up_math(const u32x4 (&W)[16], const u32 (&pj)[16], float* __restrict__ yrow, int lane) {
;     ...
;   for (int j = 0; j < 16; ++j) {
;     const float h = __uint_as_float(pj[j] << 16);
;     const f2 hh = {h, h};
; #pragma unroll
;     for (int d = 0; d < 4; ++d) {
;       f2 lo = __builtin_amdgcn_cvt_pk_f32_fp8((int)W[j][d], false);
;       f2 hi = __builtin_amdgcn_cvt_pk_f32_fp8((int)W[j][d], true);
;       y[2 * d] = lo * hh + y[2 * d];
;       y[2 * d + 1] = hi * hh + y[2 * d + 1];
;     }
;   }
	v_cvt_pk_f32_fp8_e32 v[114:115], v100
	v_cvt_pk_f32_fp8_sdwa v[120:121], v100 src0_sel:WORD_1
	v_cvt_pk_f32_fp8_e32 v[126:127], v101
	v_cvt_pk_f32_fp8_sdwa v[100:101], v101 src0_sel:WORD_1
	v_pk_fma_f32 v[114:115], v[204:205], v[114:115], v[118:119] op_sel:[1,0,0] op_sel_hi:[1,1,1]
	v_pk_fma_f32 v[118:119], v[204:205], v[120:121], v[122:123] op_sel:[1,0,0] op_sel_hi:[1,1,1]
	v_pk_fma_f32 v[120:121], v[204:205], v[126:127], v[124:125] op_sel:[1,0,0] op_sel_hi:[1,1,1]
	v_pk_fma_f32 v[100:101], v[204:205], v[100:101], v[104:105] op_sel:[1,0,0] op_sel_hi:[1,1,1]
	v_cvt_pk_f32_fp8_e32 v[104:105], v102
	v_cvt_pk_f32_fp8_sdwa v[122:123], v102 src0_sel:WORD_1
	v_cvt_pk_f32_fp8_e32 v[124:125], v103
	v_cvt_pk_f32_fp8_sdwa v[102:103], v103 src0_sel:WORD_1
	v_pk_fma_f32 v[104:105], v[204:205], v[104:105], v[108:109] op_sel:[1,0,0] op_sel_hi:[1,1,1]
	v_pk_fma_f32 v[108:109], v[204:205], v[122:123], v[112:113] op_sel:[1,0,0] op_sel_hi:[1,1,1]
	v_pk_fma_f32 v[112:113], v[204:205], v[124:125], v[116:117] op_sel:[1,0,0] op_sel_hi:[1,1,1]
	v_pk_fma_f32 v[102:103], v[204:205], v[102:103], v[106:107] op_sel:[1,0,0] op_sel_hi:[1,1,1]
	s_waitcnt vmcnt(8)
	v_cvt_pk_f32_fp8_e32 v[110:111], v96
	v_cvt_pk_f32_fp8_sdwa v[116:117], v96 src0_sel:WORD_1
	v_cvt_pk_f32_fp8_e32 v[122:123], v97
	v_cvt_pk_f32_fp8_sdwa v[96:97], v97 src0_sel:WORD_1
	v_pk_fma_f32 v[110:111], v[202:203], v[110:111], v[114:115] op_sel_hi:[0,1,1]
	v_pk_fma_f32 v[114:115], v[202:203], v[116:117], v[118:119] op_sel_hi:[0,1,1]
	v_pk_fma_f32 v[116:117], v[202:203], v[122:123], v[120:121] op_sel_hi:[0,1,1]
	v_pk_fma_f32 v[96:97], v[202:203], v[96:97], v[100:101] op_sel_hi:[0,1,1]
	v_cvt_pk_f32_fp8_e32 v[100:101], v98
	v_cvt_pk_f32_fp8_sdwa v[118:119], v98 src0_sel:WORD_1
	v_cvt_pk_f32_fp8_e32 v[120:121], v99
	v_cvt_pk_f32_fp8_sdwa v[98:99], v99 src0_sel:WORD_1
	v_pk_fma_f32 v[100:101], v[202:203], v[100:101], v[104:105] op_sel_hi:[0,1,1]
	v_pk_fma_f32 v[104:105], v[202:203], v[118:119], v[108:109] op_sel_hi:[0,1,1]
	v_pk_fma_f32 v[108:109], v[202:203], v[120:121], v[112:113] op_sel_hi:[0,1,1]
	v_pk_fma_f32 v[98:99], v[202:203], v[98:99], v[102:103] op_sel_hi:[0,1,1]
	s_waitcnt vmcnt(7)
	v_cvt_pk_f32_fp8_e32 v[106:107], v92
	v_cvt_pk_f32_fp8_sdwa v[112:113], v92 src0_sel:WORD_1
	v_cvt_pk_f32_fp8_e32 v[118:119], v93
	v_cvt_pk_f32_fp8_sdwa v[92:93], v93 src0_sel:WORD_1
	v_pk_fma_f32 v[106:107], v[202:203], v[106:107], v[110:111] op_sel:[1,0,0] op_sel_hi:[1,1,1]
	v_pk_fma_f32 v[110:111], v[202:203], v[112:113], v[114:115] op_sel:[1,0,0] op_sel_hi:[1,1,1]
	v_pk_fma_f32 v[112:113], v[202:203], v[118:119], v[116:117] op_sel:[1,0,0] op_sel_hi:[1,1,1]
	v_pk_fma_f32 v[92:93], v[202:203], v[92:93], v[96:97] op_sel:[1,0,0] op_sel_hi:[1,1,1]
	v_cvt_pk_f32_fp8_e32 v[96:97], v94
	v_cvt_pk_f32_fp8_sdwa v[114:115], v94 src0_sel:WORD_1
	v_cvt_pk_f32_fp8_e32 v[116:117], v95
	v_cvt_pk_f32_fp8_sdwa v[94:95], v95 src0_sel:WORD_1
	v_pk_fma_f32 v[96:97], v[202:203], v[96:97], v[100:101] op_sel:[1,0,0] op_sel_hi:[1,1,1]
	v_pk_fma_f32 v[100:101], v[202:203], v[114:115], v[104:105] op_sel:[1,0,0] op_sel_hi:[1,1,1]
	v_pk_fma_f32 v[104:105], v[202:203], v[116:117], v[108:109] op_sel:[1,0,0] op_sel_hi:[1,1,1]
	v_pk_fma_f32 v[94:95], v[202:203], v[94:95], v[98:99] op_sel:[1,0,0] op_sel_hi:[1,1,1]
	s_waitcnt vmcnt(6)
	v_cvt_pk_f32_fp8_e32 v[102:103], v88
	v_cvt_pk_f32_fp8_sdwa v[108:109], v88 src0_sel:WORD_1
	v_cvt_pk_f32_fp8_e32 v[114:115], v89
	v_cvt_pk_f32_fp8_sdwa v[88:89], v89 src0_sel:WORD_1
	v_pk_fma_f32 v[102:103], v[200:201], v[102:103], v[106:107] op_sel_hi:[0,1,1]
	v_pk_fma_f32 v[106:107], v[200:201], v[108:109], v[110:111] op_sel_hi:[0,1,1]
	v_pk_fma_f32 v[108:109], v[200:201], v[114:115], v[112:113] op_sel_hi:[0,1,1]
	v_pk_fma_f32 v[88:89], v[200:201], v[88:89], v[92:93] op_sel_hi:[0,1,1]
	v_cvt_pk_f32_fp8_e32 v[92:93], v90
	v_cvt_pk_f32_fp8_sdwa v[110:111], v90 src0_sel:WORD_1
	v_cvt_pk_f32_fp8_e32 v[112:113], v91
	v_cvt_pk_f32_fp8_sdwa v[90:91], v91 src0_sel:WORD_1
	v_pk_fma_f32 v[92:93], v[200:201], v[92:93], v[96:97] op_sel_hi:[0,1,1]
	v_pk_fma_f32 v[96:97], v[200:201], v[110:111], v[100:101] op_sel_hi:[0,1,1]
	v_pk_fma_f32 v[100:101], v[200:201], v[112:113], v[104:105] op_sel_hi:[0,1,1]
	v_pk_fma_f32 v[90:91], v[200:201], v[90:91], v[94:95] op_sel_hi:[0,1,1]
	s_waitcnt vmcnt(5)
	v_cvt_pk_f32_fp8_e32 v[98:99], v84
	v_cvt_pk_f32_fp8_sdwa v[104:105], v84 src0_sel:WORD_1
	v_cvt_pk_f32_fp8_e32 v[110:111], v85
	v_cvt_pk_f32_fp8_sdwa v[84:85], v85 src0_sel:WORD_1
	v_pk_fma_f32 v[98:99], v[200:201], v[98:99], v[102:103] op_sel:[1,0,0] op_sel_hi:[1,1,1]
	v_pk_fma_f32 v[102:103], v[200:201], v[104:105], v[106:107] op_sel:[1,0,0] op_sel_hi:[1,1,1]
	v_pk_fma_f32 v[104:105], v[200:201], v[110:111], v[108:109] op_sel:[1,0,0] op_sel_hi:[1,1,1]
	v_pk_fma_f32 v[84:85], v[200:201], v[84:85], v[88:89] op_sel:[1,0,0] op_sel_hi:[1,1,1]
	v_cvt_pk_f32_fp8_e32 v[88:89], v86
	v_cvt_pk_f32_fp8_sdwa v[106:107], v86 src0_sel:WORD_1
	v_cvt_pk_f32_fp8_e32 v[108:109], v87
	v_cvt_pk_f32_fp8_sdwa v[86:87], v87 src0_sel:WORD_1
	v_pk_fma_f32 v[88:89], v[200:201], v[88:89], v[92:93] op_sel:[1,0,0] op_sel_hi:[1,1,1]
	v_pk_fma_f32 v[92:93], v[200:201], v[106:107], v[96:97] op_sel:[1,0,0] op_sel_hi:[1,1,1]
	v_pk_fma_f32 v[96:97], v[200:201], v[108:109], v[100:101] op_sel:[1,0,0] op_sel_hi:[1,1,1]
	v_pk_fma_f32 v[86:87], v[200:201], v[86:87], v[90:91] op_sel:[1,0,0] op_sel_hi:[1,1,1]
	s_waitcnt vmcnt(4)
; DI void up_math(const u32x4 (&W)[16], const u32 (&pj)[16], float* __restrict__ yrow, int lane) {
;     ...
;   for (int j = 0; j < 16; ++j) {
;     const float h = __uint_as_float(pj[j] << 16);
;     const f2 hh = {h, h};
; #pragma unroll
;     for (int d = 0; d < 4; ++d) {
;       f2 lo = __builtin_amdgcn_cvt_pk_f32_fp8((int)W[j][d], false);
;       f2 hi = __builtin_amdgcn_cvt_pk_f32_fp8((int)W[j][d], true);
;       y[2 * d] = lo * hh + y[2 * d];
;       y[2 * d + 1] = hi * hh + y[2 * d + 1];
;     }
;   }
;   const bool b5 = lane & 32, b4 = lane & 16, b3 = lane & 8;
;   f2 q4[4];
; #pragma unroll
;   for (int i = 0; i < 4; ++i) {
;     f2 snd = b5 ? y[i] : y[i + 4]; f2 kp = b5 ? y[i + 4] : y[i];
;     q4[i] = f2{kp.x + __shfl_xor(snd.x, 32), kp.y + __shfl_xor(snd.y, 32)};
;   }
;   f2 r2[2];
; #pragma unroll
;   for (int i = 0; i < 2; ++i) {
;     f2 snd = b4 ? q4[i] : q4[i + 2]; f2 kp = b4 ? q4[i + 2] : q4[i];
;     r2[i] = f2{kp.x + __shfl_xor(snd.x, 16), kp.y + __shfl_xor(snd.y, 16)};
;   }
;   f2 a;
;   { f2 snd = b3 ? r2[0] : r2[1]; f2 kp = b3 ? r2[1] : r2[0]; a = f2{kp.x + __shfl_xor(snd.x, 8), kp.y + __shfl_xor(snd.y, 8)}; }
;   const int ci = (b5 ? 4 : 0) + (b4 ? 2 : 0) + (b3 ? 1 : 0);
;   *(float2*)(yrow + (lane & 7) * 16 + 2 * ci) = make_float2(a.x, a.y);
	v_cvt_pk_f32_fp8_e32 v[94:95], v80
	v_cvt_pk_f32_fp8_sdwa v[100:101], v80 src0_sel:WORD_1
	v_cvt_pk_f32_fp8_e32 v[106:107], v81
	v_cvt_pk_f32_fp8_sdwa v[80:81], v81 src0_sel:WORD_1
	v_pk_fma_f32 v[94:95], v[198:199], v[94:95], v[98:99] op_sel_hi:[0,1,1]
	v_pk_fma_f32 v[98:99], v[198:199], v[100:101], v[102:103] op_sel_hi:[0,1,1]
	v_pk_fma_f32 v[100:101], v[198:199], v[106:107], v[104:105] op_sel_hi:[0,1,1]
	v_pk_fma_f32 v[80:81], v[198:199], v[80:81], v[84:85] op_sel_hi:[0,1,1]
	v_cvt_pk_f32_fp8_e32 v[84:85], v82
	v_cvt_pk_f32_fp8_sdwa v[102:103], v82 src0_sel:WORD_1
	v_cvt_pk_f32_fp8_e32 v[104:105], v83
	v_cvt_pk_f32_fp8_sdwa v[82:83], v83 src0_sel:WORD_1
	v_pk_fma_f32 v[84:85], v[198:199], v[84:85], v[88:89] op_sel_hi:[0,1,1]
	v_pk_fma_f32 v[88:89], v[198:199], v[102:103], v[92:93] op_sel_hi:[0,1,1]
	v_pk_fma_f32 v[92:93], v[198:199], v[104:105], v[96:97] op_sel_hi:[0,1,1]
	v_pk_fma_f32 v[82:83], v[198:199], v[82:83], v[86:87] op_sel_hi:[0,1,1]
	s_waitcnt vmcnt(3)
	v_cvt_pk_f32_fp8_e32 v[90:91], v76
	v_cvt_pk_f32_fp8_sdwa v[96:97], v76 src0_sel:WORD_1
	v_cvt_pk_f32_fp8_e32 v[102:103], v77
	v_cvt_pk_f32_fp8_sdwa v[76:77], v77 src0_sel:WORD_1
	v_pk_fma_f32 v[90:91], v[198:199], v[90:91], v[94:95] op_sel:[1,0,0] op_sel_hi:[1,1,1]
	v_pk_fma_f32 v[94:95], v[198:199], v[96:97], v[98:99] op_sel:[1,0,0] op_sel_hi:[1,1,1]
	v_pk_fma_f32 v[96:97], v[198:199], v[102:103], v[100:101] op_sel:[1,0,0] op_sel_hi:[1,1,1]
	v_pk_fma_f32 v[76:77], v[198:199], v[76:77], v[80:81] op_sel:[1,0,0] op_sel_hi:[1,1,1]
	v_cvt_pk_f32_fp8_e32 v[80:81], v78
	v_cvt_pk_f32_fp8_sdwa v[98:99], v78 src0_sel:WORD_1
	v_cvt_pk_f32_fp8_e32 v[100:101], v79
	v_cvt_pk_f32_fp8_sdwa v[78:79], v79 src0_sel:WORD_1
	v_pk_fma_f32 v[80:81], v[198:199], v[80:81], v[84:85] op_sel:[1,0,0] op_sel_hi:[1,1,1]
	v_pk_fma_f32 v[84:85], v[198:199], v[98:99], v[88:89] op_sel:[1,0,0] op_sel_hi:[1,1,1]
	v_pk_fma_f32 v[88:89], v[198:199], v[100:101], v[92:93] op_sel:[1,0,0] op_sel_hi:[1,1,1]
	v_pk_fma_f32 v[78:79], v[198:199], v[78:79], v[82:83] op_sel:[1,0,0] op_sel_hi:[1,1,1]
	s_waitcnt vmcnt(2)
	v_cvt_pk_f32_fp8_e32 v[86:87], v72
	v_cvt_pk_f32_fp8_sdwa v[92:93], v72 src0_sel:WORD_1
	v_cvt_pk_f32_fp8_e32 v[98:99], v73
	v_cvt_pk_f32_fp8_sdwa v[72:73], v73 src0_sel:WORD_1
	v_pk_fma_f32 v[86:87], v[196:197], v[86:87], v[90:91] op_sel_hi:[0,1,1]
	v_pk_fma_f32 v[90:91], v[196:197], v[92:93], v[94:95] op_sel_hi:[0,1,1]
	v_pk_fma_f32 v[92:93], v[196:197], v[98:99], v[96:97] op_sel_hi:[0,1,1]
	v_pk_fma_f32 v[72:73], v[196:197], v[72:73], v[76:77] op_sel_hi:[0,1,1]
	v_cvt_pk_f32_fp8_e32 v[76:77], v74
	v_cvt_pk_f32_fp8_sdwa v[94:95], v74 src0_sel:WORD_1
	v_cvt_pk_f32_fp8_e32 v[96:97], v75
	v_cvt_pk_f32_fp8_sdwa v[74:75], v75 src0_sel:WORD_1
	v_pk_fma_f32 v[76:77], v[196:197], v[76:77], v[80:81] op_sel_hi:[0,1,1]
	v_pk_fma_f32 v[80:81], v[196:197], v[94:95], v[84:85] op_sel_hi:[0,1,1]
	v_pk_fma_f32 v[84:85], v[196:197], v[96:97], v[88:89] op_sel_hi:[0,1,1]
	v_pk_fma_f32 v[74:75], v[196:197], v[74:75], v[78:79] op_sel_hi:[0,1,1]
	s_waitcnt vmcnt(1)
	v_cvt_pk_f32_fp8_e32 v[82:83], v68
	v_cvt_pk_f32_fp8_sdwa v[88:89], v68 src0_sel:WORD_1
	v_cvt_pk_f32_fp8_e32 v[94:95], v69
	v_cvt_pk_f32_fp8_sdwa v[68:69], v69 src0_sel:WORD_1
	v_pk_fma_f32 v[82:83], v[196:197], v[82:83], v[86:87] op_sel:[1,0,0] op_sel_hi:[1,1,1]
	v_pk_fma_f32 v[86:87], v[196:197], v[88:89], v[90:91] op_sel:[1,0,0] op_sel_hi:[1,1,1]
	v_pk_fma_f32 v[68:69], v[196:197], v[68:69], v[72:73] op_sel:[1,0,0] op_sel_hi:[1,1,1]
	v_cvt_pk_f32_fp8_e32 v[72:73], v70
	v_pk_fma_f32 v[88:89], v[196:197], v[94:95], v[92:93] op_sel:[1,0,0] op_sel_hi:[1,1,1]
	v_cvt_pk_f32_fp8_sdwa v[90:91], v70 src0_sel:WORD_1
	v_cvt_pk_f32_fp8_e32 v[92:93], v71
	v_cvt_pk_f32_fp8_sdwa v[70:71], v71 src0_sel:WORD_1
	v_pk_fma_f32 v[72:73], v[196:197], v[72:73], v[76:77] op_sel:[1,0,0] op_sel_hi:[1,1,1]
	v_pk_fma_f32 v[76:77], v[196:197], v[90:91], v[80:81] op_sel:[1,0,0] op_sel_hi:[1,1,1]
	v_pk_fma_f32 v[80:81], v[196:197], v[92:93], v[84:85] op_sel:[1,0,0] op_sel_hi:[1,1,1]
	v_pk_fma_f32 v[70:71], v[196:197], v[70:71], v[74:75] op_sel:[1,0,0] op_sel_hi:[1,1,1]
	s_nop 1
	v_permlane32_swap_b32_e32 v82, v72
	v_permlane32_swap_b32_e32 v83, v73
	v_permlane32_swap_b32_e32 v86, v76
	v_permlane32_swap_b32_e32 v87, v77
	v_permlane32_swap_b32_e32 v88, v80
	v_permlane32_swap_b32_e32 v89, v81
	v_permlane32_swap_b32_e32 v68, v70
	v_permlane32_swap_b32_e32 v69, v71
	v_pk_add_f32 v[72:73], v[82:83], v[72:73]
	v_pk_add_f32 v[74:75], v[86:87], v[76:77]
	v_pk_add_f32 v[76:77], v[88:89], v[80:81]
	v_pk_add_f32 v[68:69], v[68:69], v[70:71]
	s_nop 1
	v_permlane16_swap_b32_e32 v72, v76
	v_permlane16_swap_b32_e32 v73, v77
	v_permlane16_swap_b32_e32 v74, v68
	v_permlane16_swap_b32_e32 v75, v69
	v_pk_add_f32 v[70:71], v[72:73], v[76:77]
	v_pk_add_f32 v[68:69], v[74:75], v[68:69]
	s_nop 0
	v_cndmask_b32_e64 v73, v71, v69, s[14:15]
	v_cndmask_b32_e64 v72, v70, v68, s[14:15]
	ds_bpermute_b32 v72, v143, v72
	ds_bpermute_b32 v73, v143, v73
	v_cndmask_b32_e64 v69, v69, v71, s[14:15]
	v_cndmask_b32_e64 v68, v68, v70, s[14:15]
	v_add_co_u32_e32 v70, vcc, 0x1000, v188
	s_waitcnt lgkmcnt(0)
	v_pk_add_f32 v[68:69], v[68:69], v[72:73]
	v_addc_co_u32_e32 v71, vcc, 0, v189, vcc
	global_store_dwordx2 v[70:71], v[68:69], off
	v_add_u32_e32 v145, 0x400, v145
	v_lshl_add_u64 v[188:189], v[188:189], 0, s[40:41]
	s_and_b64 vcc, exec, s[28:29]
	s_cbranch_vccnz .LBB0_814
; DI void up_issue(u32x4 (&W)[16], u32 (&pj)[16], const u32* pl, const unsigned char* wbase, int grp) {
; #pragma unroll
;   for (int j = 0; j < 16; ++j) {
;     pj[j] = pl[8 * j + grp];
;     W[j] = *(const u32x4*)(wbase + (size_t)(pj[j] >> 16) * 1024);
;   }
; }
; DI void up_math(const u32x4 (&W)[16], const u32 (&pj)[16], float* __restrict__ yrow, int lane) {
;   f2 y[8];
; #pragma unroll
;   for (int i = 0; i < 8; ++i) y[i] = f2{0.f, 0.f};
; #pragma unroll
;   for (int j = 0; j < 16; ++j) {
;     const float h = __uint_as_float(pj[j] << 16);
;     const f2 hh = {h, h};
; #pragma unroll
;     for (int d = 0; d < 4; ++d) {
;       f2 lo = __builtin_amdgcn_cvt_pk_f32_fp8((int)W[j][d], false);
;       f2 hi = __builtin_amdgcn_cvt_pk_f32_fp8((int)W[j][d], true);
;       y[2 * d] = lo * hh + y[2 * d];
;       y[2 * d + 1] = hi * hh + y[2 * d + 1];
;     }
;   }
.LBB0_827:
	v_mov_b32_e32 v210, 0
	v_mov_b32_e32 v211, 0
	v_mov_b32_e32 v208, 0
	v_mov_b32_e32 v209, 0
	v_mov_b32_e32 v206, 0
	v_mov_b32_e32 v207, 0
	ds_read_u16_d16_hi v210, v145
	ds_read_u16_d16_hi v211, v145 offset:32
	ds_read_u16_d16_hi v208, v145 offset:64
	ds_read_u16_d16_hi v209, v145 offset:96
	ds_read_u16_d16_hi v206, v145 offset:128
	ds_read_u16_d16_hi v207, v145 offset:160
	ds_read_u16_d16_hi v204, v145 offset:192
	ds_read_u16_d16_hi v205, v145 offset:224
	ds_read_u16_d16_hi v202, v145 offset:256
	ds_read_u16_d16_hi v203, v145 offset:288
	ds_read_u16_d16_hi v200, v145 offset:320
	ds_read_u16_d16_hi v201, v145 offset:352
	ds_read_u16_d16_hi v198, v145 offset:384
	ds_read_u16_d16_hi v199, v145 offset:416
	ds_read_u16_d16_hi v196, v145 offset:448
	ds_read_u16_d16_hi v197, v145 offset:480
	ds_read_u16 v128, v145 offset:2
	ds_read_u16 v124, v145 offset:34
	ds_read_u16 v120, v145 offset:66
	ds_read_u16 v116, v145 offset:98
	ds_read_u16 v112, v145 offset:130
	ds_read_u16 v108, v145 offset:162
	ds_read_u16 v104, v145 offset:194
	ds_read_u16 v100, v145 offset:226
	ds_read_u16 v96, v145 offset:258
	ds_read_u16 v92, v145 offset:290
	ds_read_u16 v88, v145 offset:322
	ds_read_u16 v84, v145 offset:354
	ds_read_u16 v80, v145 offset:386
	ds_read_u16 v76, v145 offset:418
	ds_read_u16 v72, v145 offset:450
	ds_read_u16 v68, v145 offset:482
	s_waitcnt lgkmcnt(15)
	v_lshl_add_u32 v128, v128, 10, v250
	global_load_dwordx4 v[128:131], v128, s[98:99]
	s_waitcnt lgkmcnt(14)
	v_lshl_add_u32 v124, v124, 10, v250
	global_load_dwordx4 v[124:127], v124, s[98:99]
	s_waitcnt lgkmcnt(13)
	v_lshl_add_u32 v120, v120, 10, v250
	global_load_dwordx4 v[120:123], v120, s[98:99]
	s_waitcnt lgkmcnt(12)
	v_lshl_add_u32 v116, v116, 10, v250
	global_load_dwordx4 v[116:119], v116, s[98:99]
	s_waitcnt lgkmcnt(11)
	v_lshl_add_u32 v112, v112, 10, v250
	global_load_dwordx4 v[112:115], v112, s[98:99]
	s_waitcnt lgkmcnt(10)
	v_lshl_add_u32 v108, v108, 10, v250
	global_load_dwordx4 v[108:111], v108, s[98:99]
	s_waitcnt lgkmcnt(9)
	v_lshl_add_u32 v104, v104, 10, v250
	global_load_dwordx4 v[104:107], v104, s[98:99]
	s_waitcnt lgkmcnt(8)
	v_lshl_add_u32 v100, v100, 10, v250
	global_load_dwordx4 v[100:103], v100, s[98:99]
	s_waitcnt lgkmcnt(7)
	v_lshl_add_u32 v96, v96, 10, v250
	global_load_dwordx4 v[96:99], v96, s[98:99]
	s_waitcnt lgkmcnt(6)
	v_lshl_add_u32 v92, v92, 10, v250
	global_load_dwordx4 v[92:95], v92, s[98:99]
	s_waitcnt lgkmcnt(5)
	v_lshl_add_u32 v88, v88, 10, v250
	global_load_dwordx4 v[88:91], v88, s[98:99]
	s_waitcnt lgkmcnt(4)
	v_lshl_add_u32 v84, v84, 10, v250
	global_load_dwordx4 v[84:87], v84, s[98:99]
	s_waitcnt lgkmcnt(3)
	v_lshl_add_u32 v80, v80, 10, v250
	global_load_dwordx4 v[80:83], v80, s[98:99]
	s_waitcnt lgkmcnt(2)
	v_lshl_add_u32 v76, v76, 10, v250
	global_load_dwordx4 v[76:79], v76, s[98:99]
	s_waitcnt lgkmcnt(1)
	v_lshl_add_u32 v72, v72, 10, v250
	global_load_dwordx4 v[72:75], v72, s[98:99]
	s_waitcnt lgkmcnt(0)
	v_lshl_add_u32 v68, v68, 10, v250
	global_load_dwordx4 v[68:71], v68, s[98:99]
	s_waitcnt vmcnt(31)
	v_cvt_pk_f32_fp8_e32 v[216:217], v4
	v_cvt_pk_f32_fp8_sdwa v[226:227], v4 src0_sel:WORD_1
	v_cvt_pk_f32_fp8_e32 v[228:229], v5
	v_cvt_pk_f32_fp8_sdwa v[230:231], v5 src0_sel:WORD_1
	v_cvt_pk_f32_fp8_e32 v[232:233], v6
	v_cvt_pk_f32_fp8_sdwa v[234:235], v6 src0_sel:WORD_1
	v_cvt_pk_f32_fp8_e32 v[236:237], v7
	v_cvt_pk_f32_fp8_sdwa v[238:239], v7 src0_sel:WORD_1
	s_waitcnt vmcnt(30)
	v_cvt_pk_f32_fp8_e32 v[240:241], v8
	v_cvt_pk_f32_fp8_sdwa v[242:243], v8 src0_sel:WORD_1
	v_cvt_pk_f32_fp8_e32 v[244:245], v9
	v_cvt_pk_f32_fp8_sdwa v[246:247], v9 src0_sel:WORD_1
	v_pk_fma_f32 v[216:217], v[178:179], v[216:217], 0 op_sel_hi:[0,1,0]
	v_pk_fma_f32 v[226:227], v[178:179], v[226:227], 0 op_sel_hi:[0,1,0]
	v_pk_fma_f32 v[228:229], v[178:179], v[228:229], 0 op_sel_hi:[0,1,0]
	v_pk_fma_f32 v[230:231], v[178:179], v[230:231], 0 op_sel_hi:[0,1,0]
	v_pk_fma_f32 v[232:233], v[178:179], v[232:233], 0 op_sel_hi:[0,1,0]
	v_pk_fma_f32 v[234:235], v[178:179], v[234:235], 0 op_sel_hi:[0,1,0]
	v_pk_fma_f32 v[236:237], v[178:179], v[236:237], 0 op_sel_hi:[0,1,0]
	v_pk_fma_f32 v[238:239], v[178:179], v[238:239], 0 op_sel_hi:[0,1,0]
	v_pk_fma_f32 v[216:217], v[178:179], v[240:241], v[216:217] op_sel:[1,0,0] op_sel_hi:[1,1,1]
	v_cvt_pk_f32_fp8_e32 v[240:241], v10
	v_pk_fma_f32 v[226:227], v[178:179], v[242:243], v[226:227] op_sel:[1,0,0] op_sel_hi:[1,1,1]
	v_pk_fma_f32 v[228:229], v[178:179], v[244:245], v[228:229] op_sel:[1,0,0] op_sel_hi:[1,1,1]
	v_pk_fma_f32 v[230:231], v[178:179], v[246:247], v[230:231] op_sel:[1,0,0] op_sel_hi:[1,1,1]
	v_cvt_pk_f32_fp8_sdwa v[242:243], v10 src0_sel:WORD_1
	v_cvt_pk_f32_fp8_e32 v[244:245], v11
	v_cvt_pk_f32_fp8_sdwa v[246:247], v11 src0_sel:WORD_1
	v_pk_fma_f32 v[232:233], v[178:179], v[240:241], v[232:233] op_sel:[1,0,0] op_sel_hi:[1,1,1]
	s_waitcnt vmcnt(29)
	v_cvt_pk_f32_fp8_e32 v[240:241], v12
	v_pk_fma_f32 v[234:235], v[178:179], v[242:243], v[234:235] op_sel:[1,0,0] op_sel_hi:[1,1,1]
	v_pk_fma_f32 v[236:237], v[178:179], v[244:245], v[236:237] op_sel:[1,0,0] op_sel_hi:[1,1,1]
	v_pk_fma_f32 v[238:239], v[178:179], v[246:247], v[238:239] op_sel:[1,0,0] op_sel_hi:[1,1,1]
	v_cvt_pk_f32_fp8_sdwa v[242:243], v12 src0_sel:WORD_1
	v_cvt_pk_f32_fp8_e32 v[244:245], v13
	v_cvt_pk_f32_fp8_sdwa v[246:247], v13 src0_sel:WORD_1
	v_pk_fma_f32 v[216:217], v[180:181], v[240:241], v[216:217] op_sel_hi:[0,1,1]
	v_cvt_pk_f32_fp8_e32 v[240:241], v14
	v_pk_fma_f32 v[226:227], v[180:181], v[242:243], v[226:227] op_sel_hi:[0,1,1]
	v_pk_fma_f32 v[228:229], v[180:181], v[244:245], v[228:229] op_sel_hi:[0,1,1]
	v_pk_fma_f32 v[230:231], v[180:181], v[246:247], v[230:231] op_sel_hi:[0,1,1]
	v_cvt_pk_f32_fp8_sdwa v[242:243], v14 src0_sel:WORD_1
	v_cvt_pk_f32_fp8_e32 v[244:245], v15
	v_cvt_pk_f32_fp8_sdwa v[246:247], v15 src0_sel:WORD_1
	v_pk_fma_f32 v[232:233], v[180:181], v[240:241], v[232:233] op_sel_hi:[0,1,1]
	s_waitcnt vmcnt(28)
; DI void up_math(const u32x4 (&W)[16], const u32 (&pj)[16], float* __restrict__ yrow, int lane) {
;     ...
;   for (int j = 0; j < 16; ++j) {
;     const float h = __uint_as_float(pj[j] << 16);
;     const f2 hh = {h, h};
; #pragma unroll
;     for (int d = 0; d < 4; ++d) {
;       f2 lo = __builtin_amdgcn_cvt_pk_f32_fp8((int)W[j][d], false);
;       f2 hi = __builtin_amdgcn_cvt_pk_f32_fp8((int)W[j][d], true);
;       y[2 * d] = lo * hh + y[2 * d];
;       y[2 * d + 1] = hi * hh + y[2 * d + 1];
;     }
;   }
	v_cvt_pk_f32_fp8_e32 v[240:241], v16
	v_pk_fma_f32 v[234:235], v[180:181], v[242:243], v[234:235] op_sel_hi:[0,1,1]
	v_pk_fma_f32 v[236:237], v[180:181], v[244:245], v[236:237] op_sel_hi:[0,1,1]
	v_pk_fma_f32 v[238:239], v[180:181], v[246:247], v[238:239] op_sel_hi:[0,1,1]
	v_cvt_pk_f32_fp8_sdwa v[242:243], v16 src0_sel:WORD_1
	v_cvt_pk_f32_fp8_e32 v[244:245], v17
	v_cvt_pk_f32_fp8_sdwa v[246:247], v17 src0_sel:WORD_1
	v_pk_fma_f32 v[216:217], v[180:181], v[240:241], v[216:217] op_sel:[1,0,0] op_sel_hi:[1,1,1]
	v_cvt_pk_f32_fp8_e32 v[240:241], v18
	v_pk_fma_f32 v[226:227], v[180:181], v[242:243], v[226:227] op_sel:[1,0,0] op_sel_hi:[1,1,1]
	v_pk_fma_f32 v[228:229], v[180:181], v[244:245], v[228:229] op_sel:[1,0,0] op_sel_hi:[1,1,1]
	v_pk_fma_f32 v[230:231], v[180:181], v[246:247], v[230:231] op_sel:[1,0,0] op_sel_hi:[1,1,1]
	v_cvt_pk_f32_fp8_sdwa v[242:243], v18 src0_sel:WORD_1
	v_cvt_pk_f32_fp8_e32 v[244:245], v19
	v_cvt_pk_f32_fp8_sdwa v[246:247], v19 src0_sel:WORD_1
	v_pk_fma_f32 v[232:233], v[180:181], v[240:241], v[232:233] op_sel:[1,0,0] op_sel_hi:[1,1,1]
	s_waitcnt vmcnt(27)
	v_cvt_pk_f32_fp8_e32 v[240:241], v20
	v_pk_fma_f32 v[234:235], v[180:181], v[242:243], v[234:235] op_sel:[1,0,0] op_sel_hi:[1,1,1]
	v_pk_fma_f32 v[236:237], v[180:181], v[244:245], v[236:237] op_sel:[1,0,0] op_sel_hi:[1,1,1]
	v_pk_fma_f32 v[238:239], v[180:181], v[246:247], v[238:239] op_sel:[1,0,0] op_sel_hi:[1,1,1]
	v_cvt_pk_f32_fp8_sdwa v[242:243], v20 src0_sel:WORD_1
	v_cvt_pk_f32_fp8_e32 v[244:245], v21
	v_cvt_pk_f32_fp8_sdwa v[246:247], v21 src0_sel:WORD_1
	v_pk_fma_f32 v[216:217], v[182:183], v[240:241], v[216:217] op_sel_hi:[0,1,1]
	v_cvt_pk_f32_fp8_e32 v[240:241], v22
	v_pk_fma_f32 v[226:227], v[182:183], v[242:243], v[226:227] op_sel_hi:[0,1,1]
	v_pk_fma_f32 v[228:229], v[182:183], v[244:245], v[228:229] op_sel_hi:[0,1,1]
	v_pk_fma_f32 v[230:231], v[182:183], v[246:247], v[230:231] op_sel_hi:[0,1,1]
	v_cvt_pk_f32_fp8_sdwa v[242:243], v22 src0_sel:WORD_1
	v_cvt_pk_f32_fp8_e32 v[244:245], v23
	v_cvt_pk_f32_fp8_sdwa v[246:247], v23 src0_sel:WORD_1
	v_pk_fma_f32 v[232:233], v[182:183], v[240:241], v[232:233] op_sel_hi:[0,1,1]
	s_waitcnt vmcnt(26)
	v_cvt_pk_f32_fp8_e32 v[240:241], v24
	v_pk_fma_f32 v[234:235], v[182:183], v[242:243], v[234:235] op_sel_hi:[0,1,1]
	v_pk_fma_f32 v[236:237], v[182:183], v[244:245], v[236:237] op_sel_hi:[0,1,1]
	v_pk_fma_f32 v[238:239], v[182:183], v[246:247], v[238:239] op_sel_hi:[0,1,1]
	v_cvt_pk_f32_fp8_sdwa v[242:243], v24 src0_sel:WORD_1
	v_cvt_pk_f32_fp8_e32 v[244:245], v25
	v_cvt_pk_f32_fp8_sdwa v[246:247], v25 src0_sel:WORD_1
	v_pk_fma_f32 v[216:217], v[182:183], v[240:241], v[216:217] op_sel:[1,0,0] op_sel_hi:[1,1,1]
	v_cvt_pk_f32_fp8_e32 v[240:241], v26
	v_pk_fma_f32 v[226:227], v[182:183], v[242:243], v[226:227] op_sel:[1,0,0] op_sel_hi:[1,1,1]
	v_pk_fma_f32 v[228:229], v[182:183], v[244:245], v[228:229] op_sel:[1,0,0] op_sel_hi:[1,1,1]
	v_pk_fma_f32 v[230:231], v[182:183], v[246:247], v[230:231] op_sel:[1,0,0] op_sel_hi:[1,1,1]
	v_cvt_pk_f32_fp8_sdwa v[242:243], v26 src0_sel:WORD_1
	v_cvt_pk_f32_fp8_e32 v[244:245], v27
	v_cvt_pk_f32_fp8_sdwa v[246:247], v27 src0_sel:WORD_1
	v_pk_fma_f32 v[232:233], v[182:183], v[240:241], v[232:233] op_sel:[1,0,0] op_sel_hi:[1,1,1]
	s_waitcnt vmcnt(25)
	v_cvt_pk_f32_fp8_e32 v[240:241], v28
	v_pk_fma_f32 v[234:235], v[182:183], v[242:243], v[234:235] op_sel:[1,0,0] op_sel_hi:[1,1,1]
	v_pk_fma_f32 v[236:237], v[182:183], v[244:245], v[236:237] op_sel:[1,0,0] op_sel_hi:[1,1,1]
	v_pk_fma_f32 v[238:239], v[182:183], v[246:247], v[238:239] op_sel:[1,0,0] op_sel_hi:[1,1,1]
	v_cvt_pk_f32_fp8_sdwa v[242:243], v28 src0_sel:WORD_1
	v_cvt_pk_f32_fp8_e32 v[244:245], v29
	v_cvt_pk_f32_fp8_sdwa v[246:247], v29 src0_sel:WORD_1
	v_pk_fma_f32 v[216:217], v[184:185], v[240:241], v[216:217] op_sel_hi:[0,1,1]
	v_cvt_pk_f32_fp8_e32 v[240:241], v30
	v_pk_fma_f32 v[226:227], v[184:185], v[242:243], v[226:227] op_sel_hi:[0,1,1]
	v_pk_fma_f32 v[228:229], v[184:185], v[244:245], v[228:229] op_sel_hi:[0,1,1]
	v_pk_fma_f32 v[230:231], v[184:185], v[246:247], v[230:231] op_sel_hi:[0,1,1]
	v_cvt_pk_f32_fp8_sdwa v[242:243], v30 src0_sel:WORD_1
	v_cvt_pk_f32_fp8_e32 v[244:245], v31
	v_cvt_pk_f32_fp8_sdwa v[246:247], v31 src0_sel:WORD_1
	v_pk_fma_f32 v[232:233], v[184:185], v[240:241], v[232:233] op_sel_hi:[0,1,1]
	s_waitcnt vmcnt(24)
	v_cvt_pk_f32_fp8_e32 v[240:241], v32
	v_pk_fma_f32 v[234:235], v[184:185], v[242:243], v[234:235] op_sel_hi:[0,1,1]
	v_pk_fma_f32 v[236:237], v[184:185], v[244:245], v[236:237] op_sel_hi:[0,1,1]
	v_pk_fma_f32 v[238:239], v[184:185], v[246:247], v[238:239] op_sel_hi:[0,1,1]
	v_cvt_pk_f32_fp8_sdwa v[242:243], v32 src0_sel:WORD_1
	v_cvt_pk_f32_fp8_e32 v[244:245], v33
	v_cvt_pk_f32_fp8_sdwa v[246:247], v33 src0_sel:WORD_1
	v_pk_fma_f32 v[216:217], v[184:185], v[240:241], v[216:217] op_sel:[1,0,0] op_sel_hi:[1,1,1]
	v_cvt_pk_f32_fp8_e32 v[240:241], v34
	v_pk_fma_f32 v[226:227], v[184:185], v[242:243], v[226:227] op_sel:[1,0,0] op_sel_hi:[1,1,1]
	v_pk_fma_f32 v[228:229], v[184:185], v[244:245], v[228:229] op_sel:[1,0,0] op_sel_hi:[1,1,1]
	v_pk_fma_f32 v[230:231], v[184:185], v[246:247], v[230:231] op_sel:[1,0,0] op_sel_hi:[1,1,1]
	v_cvt_pk_f32_fp8_sdwa v[242:243], v34 src0_sel:WORD_1
	v_cvt_pk_f32_fp8_e32 v[244:245], v35
	v_cvt_pk_f32_fp8_sdwa v[246:247], v35 src0_sel:WORD_1
	v_pk_fma_f32 v[232:233], v[184:185], v[240:241], v[232:233] op_sel:[1,0,0] op_sel_hi:[1,1,1]
	s_waitcnt vmcnt(23)
; DI void up_math(const u32x4 (&W)[16], const u32 (&pj)[16], float* __restrict__ yrow, int lane) {
;     ...
;   for (int j = 0; j < 16; ++j) {
;     const float h = __uint_as_float(pj[j] << 16);
;     const f2 hh = {h, h};
; #pragma unroll
;     for (int d = 0; d < 4; ++d) {
;       f2 lo = __builtin_amdgcn_cvt_pk_f32_fp8((int)W[j][d], false);
;       f2 hi = __builtin_amdgcn_cvt_pk_f32_fp8((int)W[j][d], true);
;       y[2 * d] = lo * hh + y[2 * d];
;       y[2 * d + 1] = hi * hh + y[2 * d + 1];
;     }
;   }
	v_cvt_pk_f32_fp8_e32 v[240:241], v36
	v_pk_fma_f32 v[234:235], v[184:185], v[242:243], v[234:235] op_sel:[1,0,0] op_sel_hi:[1,1,1]
	v_pk_fma_f32 v[236:237], v[184:185], v[244:245], v[236:237] op_sel:[1,0,0] op_sel_hi:[1,1,1]
	v_pk_fma_f32 v[238:239], v[184:185], v[246:247], v[238:239] op_sel:[1,0,0] op_sel_hi:[1,1,1]
	v_cvt_pk_f32_fp8_sdwa v[242:243], v36 src0_sel:WORD_1
	v_cvt_pk_f32_fp8_e32 v[244:245], v37
	v_cvt_pk_f32_fp8_sdwa v[246:247], v37 src0_sel:WORD_1
	v_pk_fma_f32 v[216:217], v[186:187], v[240:241], v[216:217] op_sel_hi:[0,1,1]
	v_cvt_pk_f32_fp8_e32 v[240:241], v38
	v_pk_fma_f32 v[226:227], v[186:187], v[242:243], v[226:227] op_sel_hi:[0,1,1]
	v_pk_fma_f32 v[228:229], v[186:187], v[244:245], v[228:229] op_sel_hi:[0,1,1]
	v_pk_fma_f32 v[230:231], v[186:187], v[246:247], v[230:231] op_sel_hi:[0,1,1]
	v_cvt_pk_f32_fp8_sdwa v[242:243], v38 src0_sel:WORD_1
	v_cvt_pk_f32_fp8_e32 v[244:245], v39
	v_cvt_pk_f32_fp8_sdwa v[246:247], v39 src0_sel:WORD_1
	v_pk_fma_f32 v[232:233], v[186:187], v[240:241], v[232:233] op_sel_hi:[0,1,1]
	s_waitcnt vmcnt(22)
	v_cvt_pk_f32_fp8_e32 v[240:241], v40
	v_pk_fma_f32 v[234:235], v[186:187], v[242:243], v[234:235] op_sel_hi:[0,1,1]
	v_pk_fma_f32 v[236:237], v[186:187], v[244:245], v[236:237] op_sel_hi:[0,1,1]
	v_pk_fma_f32 v[238:239], v[186:187], v[246:247], v[238:239] op_sel_hi:[0,1,1]
	v_cvt_pk_f32_fp8_sdwa v[242:243], v40 src0_sel:WORD_1
	v_cvt_pk_f32_fp8_e32 v[244:245], v41
	v_cvt_pk_f32_fp8_sdwa v[246:247], v41 src0_sel:WORD_1
	v_pk_fma_f32 v[216:217], v[186:187], v[240:241], v[216:217] op_sel:[1,0,0] op_sel_hi:[1,1,1]
	v_cvt_pk_f32_fp8_e32 v[240:241], v42
	v_pk_fma_f32 v[226:227], v[186:187], v[242:243], v[226:227] op_sel:[1,0,0] op_sel_hi:[1,1,1]
	v_pk_fma_f32 v[228:229], v[186:187], v[244:245], v[228:229] op_sel:[1,0,0] op_sel_hi:[1,1,1]
	v_pk_fma_f32 v[230:231], v[186:187], v[246:247], v[230:231] op_sel:[1,0,0] op_sel_hi:[1,1,1]
	v_cvt_pk_f32_fp8_sdwa v[242:243], v42 src0_sel:WORD_1
	v_cvt_pk_f32_fp8_e32 v[244:245], v43
	v_cvt_pk_f32_fp8_sdwa v[246:247], v43 src0_sel:WORD_1
	v_pk_fma_f32 v[232:233], v[186:187], v[240:241], v[232:233] op_sel:[1,0,0] op_sel_hi:[1,1,1]
	s_waitcnt vmcnt(21)
	v_cvt_pk_f32_fp8_e32 v[240:241], v44
	v_pk_fma_f32 v[234:235], v[186:187], v[242:243], v[234:235] op_sel:[1,0,0] op_sel_hi:[1,1,1]
	v_pk_fma_f32 v[236:237], v[186:187], v[244:245], v[236:237] op_sel:[1,0,0] op_sel_hi:[1,1,1]
	v_pk_fma_f32 v[238:239], v[186:187], v[246:247], v[238:239] op_sel:[1,0,0] op_sel_hi:[1,1,1]
	v_cvt_pk_f32_fp8_sdwa v[242:243], v44 src0_sel:WORD_1
	v_cvt_pk_f32_fp8_e32 v[244:245], v45
	v_cvt_pk_f32_fp8_sdwa v[246:247], v45 src0_sel:WORD_1
	v_pk_fma_f32 v[216:217], v[190:191], v[240:241], v[216:217] op_sel_hi:[0,1,1]
	v_cvt_pk_f32_fp8_e32 v[240:241], v46
	v_pk_fma_f32 v[226:227], v[190:191], v[242:243], v[226:227] op_sel_hi:[0,1,1]
	v_pk_fma_f32 v[228:229], v[190:191], v[244:245], v[228:229] op_sel_hi:[0,1,1]
	v_pk_fma_f32 v[230:231], v[190:191], v[246:247], v[230:231] op_sel_hi:[0,1,1]
	v_cvt_pk_f32_fp8_sdwa v[242:243], v46 src0_sel:WORD_1
	v_cvt_pk_f32_fp8_e32 v[244:245], v47
	v_cvt_pk_f32_fp8_sdwa v[246:247], v47 src0_sel:WORD_1
	v_pk_fma_f32 v[232:233], v[190:191], v[240:241], v[232:233] op_sel_hi:[0,1,1]
	s_waitcnt vmcnt(20)
	v_cvt_pk_f32_fp8_e32 v[240:241], v48
	v_pk_fma_f32 v[234:235], v[190:191], v[242:243], v[234:235] op_sel_hi:[0,1,1]
	v_pk_fma_f32 v[236:237], v[190:191], v[244:245], v[236:237] op_sel_hi:[0,1,1]
	v_pk_fma_f32 v[238:239], v[190:191], v[246:247], v[238:239] op_sel_hi:[0,1,1]
	v_cvt_pk_f32_fp8_sdwa v[242:243], v48 src0_sel:WORD_1
	v_cvt_pk_f32_fp8_e32 v[244:245], v49
	v_cvt_pk_f32_fp8_sdwa v[246:247], v49 src0_sel:WORD_1
	v_pk_fma_f32 v[216:217], v[190:191], v[240:241], v[216:217] op_sel:[1,0,0] op_sel_hi:[1,1,1]
	v_cvt_pk_f32_fp8_e32 v[240:241], v50
	v_pk_fma_f32 v[226:227], v[190:191], v[242:243], v[226:227] op_sel:[1,0,0] op_sel_hi:[1,1,1]
	v_pk_fma_f32 v[228:229], v[190:191], v[244:245], v[228:229] op_sel:[1,0,0] op_sel_hi:[1,1,1]
	v_pk_fma_f32 v[230:231], v[190:191], v[246:247], v[230:231] op_sel:[1,0,0] op_sel_hi:[1,1,1]
	v_cvt_pk_f32_fp8_sdwa v[242:243], v50 src0_sel:WORD_1
	v_cvt_pk_f32_fp8_e32 v[244:245], v51
	v_cvt_pk_f32_fp8_sdwa v[246:247], v51 src0_sel:WORD_1
	v_pk_fma_f32 v[232:233], v[190:191], v[240:241], v[232:233] op_sel:[1,0,0] op_sel_hi:[1,1,1]
	s_waitcnt vmcnt(19)
	v_cvt_pk_f32_fp8_e32 v[240:241], v52
	v_pk_fma_f32 v[234:235], v[190:191], v[242:243], v[234:235] op_sel:[1,0,0] op_sel_hi:[1,1,1]
	v_pk_fma_f32 v[236:237], v[190:191], v[244:245], v[236:237] op_sel:[1,0,0] op_sel_hi:[1,1,1]
	v_pk_fma_f32 v[238:239], v[190:191], v[246:247], v[238:239] op_sel:[1,0,0] op_sel_hi:[1,1,1]
	v_cvt_pk_f32_fp8_sdwa v[242:243], v52 src0_sel:WORD_1
	v_cvt_pk_f32_fp8_e32 v[244:245], v53
	v_cvt_pk_f32_fp8_sdwa v[246:247], v53 src0_sel:WORD_1
	v_pk_fma_f32 v[216:217], v[192:193], v[240:241], v[216:217] op_sel_hi:[0,1,1]
	v_cvt_pk_f32_fp8_e32 v[240:241], v54
	v_pk_fma_f32 v[226:227], v[192:193], v[242:243], v[226:227] op_sel_hi:[0,1,1]
	v_pk_fma_f32 v[228:229], v[192:193], v[244:245], v[228:229] op_sel_hi:[0,1,1]
	v_pk_fma_f32 v[230:231], v[192:193], v[246:247], v[230:231] op_sel_hi:[0,1,1]
	v_cvt_pk_f32_fp8_sdwa v[242:243], v54 src0_sel:WORD_1
	v_cvt_pk_f32_fp8_e32 v[244:245], v55
	v_cvt_pk_f32_fp8_sdwa v[246:247], v55 src0_sel:WORD_1
	v_pk_fma_f32 v[232:233], v[192:193], v[240:241], v[232:233] op_sel_hi:[0,1,1]
	s_waitcnt vmcnt(18)
; DI void up_math(const u32x4 (&W)[16], const u32 (&pj)[16], float* __restrict__ yrow, int lane) {
;     ...
;   for (int j = 0; j < 16; ++j) {
;     const float h = __uint_as_float(pj[j] << 16);
;     const f2 hh = {h, h};
; #pragma unroll
;     for (int d = 0; d < 4; ++d) {
;       f2 lo = __builtin_amdgcn_cvt_pk_f32_fp8((int)W[j][d], false);
;       f2 hi = __builtin_amdgcn_cvt_pk_f32_fp8((int)W[j][d], true);
;       y[2 * d] = lo * hh + y[2 * d];
;       y[2 * d + 1] = hi * hh + y[2 * d + 1];
;     }
;   }
;   const bool b5 = lane & 32, b4 = lane & 16, b3 = lane & 8;
;   f2 q4[4];
; #pragma unroll
;   for (int i = 0; i < 4; ++i) {
;     f2 snd = b5 ? y[i] : y[i + 4]; f2 kp = b5 ? y[i + 4] : y[i];
;     q4[i] = f2{kp.x + __shfl_xor(snd.x, 32), kp.y + __shfl_xor(snd.y, 32)};
;   }
;   f2 r2[2];
; #pragma unroll
;   for (int i = 0; i < 2; ++i) {
;     f2 snd = b4 ? q4[i] : q4[i + 2]; f2 kp = b4 ? q4[i + 2] : q4[i];
;     r2[i] = f2{kp.x + __shfl_xor(snd.x, 16), kp.y + __shfl_xor(snd.y, 16)};
;   }
;   f2 a;
;   { f2 snd = b3 ? r2[0] : r2[1]; f2 kp = b3 ? r2[1] : r2[0]; a = f2{kp.x + __shfl_xor(snd.x, 8), kp.y + __shfl_xor(snd.y, 8)}; }
;   const int ci = (b5 ? 4 : 0) + (b4 ? 2 : 0) + (b3 ? 1 : 0);
;   *(float2*)(yrow + (lane & 7) * 16 + 2 * ci) = make_float2(a.x, a.y);
	v_cvt_pk_f32_fp8_e32 v[240:241], v56
	v_pk_fma_f32 v[234:235], v[192:193], v[242:243], v[234:235] op_sel_hi:[0,1,1]
	v_pk_fma_f32 v[236:237], v[192:193], v[244:245], v[236:237] op_sel_hi:[0,1,1]
	v_pk_fma_f32 v[238:239], v[192:193], v[246:247], v[238:239] op_sel_hi:[0,1,1]
	v_cvt_pk_f32_fp8_sdwa v[242:243], v56 src0_sel:WORD_1
	v_cvt_pk_f32_fp8_e32 v[244:245], v57
	v_cvt_pk_f32_fp8_sdwa v[246:247], v57 src0_sel:WORD_1
	v_pk_fma_f32 v[216:217], v[192:193], v[240:241], v[216:217] op_sel:[1,0,0] op_sel_hi:[1,1,1]
	v_cvt_pk_f32_fp8_e32 v[240:241], v58
	v_pk_fma_f32 v[226:227], v[192:193], v[242:243], v[226:227] op_sel:[1,0,0] op_sel_hi:[1,1,1]
	v_pk_fma_f32 v[228:229], v[192:193], v[244:245], v[228:229] op_sel:[1,0,0] op_sel_hi:[1,1,1]
	v_pk_fma_f32 v[230:231], v[192:193], v[246:247], v[230:231] op_sel:[1,0,0] op_sel_hi:[1,1,1]
	v_cvt_pk_f32_fp8_sdwa v[242:243], v58 src0_sel:WORD_1
	v_cvt_pk_f32_fp8_e32 v[244:245], v59
	v_cvt_pk_f32_fp8_sdwa v[246:247], v59 src0_sel:WORD_1
	v_pk_fma_f32 v[232:233], v[192:193], v[240:241], v[232:233] op_sel:[1,0,0] op_sel_hi:[1,1,1]
	s_waitcnt vmcnt(17)
	v_cvt_pk_f32_fp8_e32 v[240:241], v60
	v_pk_fma_f32 v[234:235], v[192:193], v[242:243], v[234:235] op_sel:[1,0,0] op_sel_hi:[1,1,1]
	v_pk_fma_f32 v[236:237], v[192:193], v[244:245], v[236:237] op_sel:[1,0,0] op_sel_hi:[1,1,1]
	v_pk_fma_f32 v[238:239], v[192:193], v[246:247], v[238:239] op_sel:[1,0,0] op_sel_hi:[1,1,1]
	v_cvt_pk_f32_fp8_sdwa v[242:243], v60 src0_sel:WORD_1
	v_cvt_pk_f32_fp8_e32 v[244:245], v61
	v_cvt_pk_f32_fp8_sdwa v[246:247], v61 src0_sel:WORD_1
	v_pk_fma_f32 v[216:217], v[194:195], v[240:241], v[216:217] op_sel_hi:[0,1,1]
	v_cvt_pk_f32_fp8_e32 v[240:241], v62
	v_pk_fma_f32 v[226:227], v[194:195], v[242:243], v[226:227] op_sel_hi:[0,1,1]
	v_pk_fma_f32 v[228:229], v[194:195], v[244:245], v[228:229] op_sel_hi:[0,1,1]
	v_pk_fma_f32 v[230:231], v[194:195], v[246:247], v[230:231] op_sel_hi:[0,1,1]
	v_cvt_pk_f32_fp8_sdwa v[242:243], v62 src0_sel:WORD_1
	v_cvt_pk_f32_fp8_e32 v[244:245], v63
	v_cvt_pk_f32_fp8_sdwa v[246:247], v63 src0_sel:WORD_1
	v_pk_fma_f32 v[232:233], v[194:195], v[240:241], v[232:233] op_sel_hi:[0,1,1]
	s_waitcnt vmcnt(16)
	v_cvt_pk_f32_fp8_e32 v[240:241], v64
	v_pk_fma_f32 v[234:235], v[194:195], v[242:243], v[234:235] op_sel_hi:[0,1,1]
	v_pk_fma_f32 v[236:237], v[194:195], v[244:245], v[236:237] op_sel_hi:[0,1,1]
	v_pk_fma_f32 v[238:239], v[194:195], v[246:247], v[238:239] op_sel_hi:[0,1,1]
	v_cvt_pk_f32_fp8_sdwa v[242:243], v64 src0_sel:WORD_1
	v_cvt_pk_f32_fp8_e32 v[244:245], v65
	v_cvt_pk_f32_fp8_sdwa v[246:247], v65 src0_sel:WORD_1
	v_pk_fma_f32 v[216:217], v[194:195], v[240:241], v[216:217] op_sel:[1,0,0] op_sel_hi:[1,1,1]
	v_cvt_pk_f32_fp8_e32 v[240:241], v66
	v_pk_fma_f32 v[226:227], v[194:195], v[242:243], v[226:227] op_sel:[1,0,0] op_sel_hi:[1,1,1]
	v_pk_fma_f32 v[228:229], v[194:195], v[244:245], v[228:229] op_sel:[1,0,0] op_sel_hi:[1,1,1]
	v_pk_fma_f32 v[230:231], v[194:195], v[246:247], v[230:231] op_sel:[1,0,0] op_sel_hi:[1,1,1]
	v_cvt_pk_f32_fp8_sdwa v[242:243], v66 src0_sel:WORD_1
	v_cvt_pk_f32_fp8_e32 v[244:245], v67
	v_cvt_pk_f32_fp8_sdwa v[246:247], v67 src0_sel:WORD_1
	v_pk_fma_f32 v[232:233], v[194:195], v[240:241], v[232:233] op_sel:[1,0,0] op_sel_hi:[1,1,1]
	v_pk_fma_f32 v[234:235], v[194:195], v[242:243], v[234:235] op_sel:[1,0,0] op_sel_hi:[1,1,1]
	v_pk_fma_f32 v[236:237], v[194:195], v[244:245], v[236:237] op_sel:[1,0,0] op_sel_hi:[1,1,1]
	v_pk_fma_f32 v[238:239], v[194:195], v[246:247], v[238:239] op_sel:[1,0,0] op_sel_hi:[1,1,1]
	s_nop 1
	v_permlane32_swap_b32_e32 v216, v232
	v_permlane32_swap_b32_e32 v217, v233
	v_permlane32_swap_b32_e32 v228, v236
	v_permlane32_swap_b32_e32 v229, v237
	v_permlane32_swap_b32_e32 v226, v234
	v_permlane32_swap_b32_e32 v227, v235
	v_permlane32_swap_b32_e32 v230, v238
	v_permlane32_swap_b32_e32 v231, v239
	v_pk_add_f32 v[216:217], v[216:217], v[232:233]
	v_pk_add_f32 v[228:229], v[228:229], v[236:237]
	v_pk_add_f32 v[226:227], v[226:227], v[234:235]
	v_pk_add_f32 v[230:231], v[230:231], v[238:239]
	s_nop 1
	v_permlane16_swap_b32_e32 v216, v228
	v_permlane16_swap_b32_e32 v217, v229
	v_permlane16_swap_b32_e32 v226, v230
	v_permlane16_swap_b32_e32 v227, v231
	v_pk_add_f32 v[216:217], v[216:217], v[228:229]
	v_pk_add_f32 v[226:227], v[226:227], v[230:231]
	s_nop 0
	v_cndmask_b32_e64 v132, v217, v227, s[14:15]
	v_cndmask_b32_e64 v147, v216, v226, s[14:15]
	ds_bpermute_b32 v228, v143, v147
	ds_bpermute_b32 v229, v143, v132
	v_cndmask_b32_e64 v217, v227, v217, s[14:15]
	v_cndmask_b32_e64 v216, v226, v216, s[14:15]
	s_waitcnt lgkmcnt(0)
	v_pk_add_f32 v[216:217], v[216:217], v[228:229]
	global_store_dwordx2 v[188:189], v[216:217], off
	s_cmp_gt_u32 s44, 13
	s_cselect_b64 s[28:29], -1, 0
	s_and_b64 vcc, exec, s[28:29]
	s_cbranch_vccnz .LBB0_826
; DI void up_issue(u32x4 (&W)[16], u32 (&pj)[16], const u32* pl, const unsigned char* wbase, int grp) {
; #pragma unroll
;   for (int j = 0; j < 16; ++j) {
;     pj[j] = pl[8 * j + grp];
;     W[j] = *(const u32x4*)(wbase + (size_t)(pj[j] >> 16) * 1024);
;   }
; }
	ds_read_u16_d16_hi v178, v145 offset:512
	ds_read_u16_d16_hi v179, v145 offset:544
	ds_read_u16_d16_hi v180, v145 offset:576
	ds_read_u16_d16_hi v181, v145 offset:608
	ds_read_u16_d16_hi v182, v145 offset:640
	ds_read_u16_d16_hi v183, v145 offset:672
	ds_read_u16_d16_hi v184, v145 offset:704
	ds_read_u16_d16_hi v185, v145 offset:736
	ds_read_u16_d16_hi v186, v145 offset:768
	ds_read_u16_d16_hi v187, v145 offset:800
	ds_read_u16_d16_hi v190, v145 offset:832
	ds_read_u16_d16_hi v191, v145 offset:864
	ds_read_u16_d16_hi v192, v145 offset:896
	ds_read_u16_d16_hi v193, v145 offset:928
	ds_read_u16_d16_hi v194, v145 offset:960
	ds_read_u16_d16_hi v195, v145 offset:992
	ds_read_u16 v4, v145 offset:514
	ds_read_u16 v8, v145 offset:546
	ds_read_u16 v12, v145 offset:578
	ds_read_u16 v16, v145 offset:610
	ds_read_u16 v20, v145 offset:642
	ds_read_u16 v24, v145 offset:674
	ds_read_u16 v28, v145 offset:706
	ds_read_u16 v32, v145 offset:738
	ds_read_u16 v36, v145 offset:770
	ds_read_u16 v40, v145 offset:802
	ds_read_u16 v44, v145 offset:834
	ds_read_u16 v48, v145 offset:866
	ds_read_u16 v52, v145 offset:898
	ds_read_u16 v56, v145 offset:930
	ds_read_u16 v60, v145 offset:962
	ds_read_u16 v64, v145 offset:994
	s_waitcnt lgkmcnt(15)
	v_lshl_add_u32 v4, v4, 10, v250
	global_load_dwordx4 v[4:7], v4, s[98:99]
	s_waitcnt lgkmcnt(14)
	v_lshl_add_u32 v8, v8, 10, v250
	global_load_dwordx4 v[8:11], v8, s[98:99]
	s_waitcnt lgkmcnt(13)
	v_lshl_add_u32 v12, v12, 10, v250
	global_load_dwordx4 v[12:15], v12, s[98:99]
	s_waitcnt lgkmcnt(12)
	v_lshl_add_u32 v16, v16, 10, v250
	global_load_dwordx4 v[16:19], v16, s[98:99]
	s_waitcnt lgkmcnt(11)
	v_lshl_add_u32 v20, v20, 10, v250
	global_load_dwordx4 v[20:23], v20, s[98:99]
	s_waitcnt lgkmcnt(10)
	v_lshl_add_u32 v24, v24, 10, v250
	global_load_dwordx4 v[24:27], v24, s[98:99]
	s_waitcnt lgkmcnt(9)
	v_lshl_add_u32 v28, v28, 10, v250
	global_load_dwordx4 v[28:31], v28, s[98:99]
	s_waitcnt lgkmcnt(8)
	v_lshl_add_u32 v32, v32, 10, v250
	global_load_dwordx4 v[32:35], v32, s[98:99]
	s_waitcnt lgkmcnt(7)
	v_lshl_add_u32 v36, v36, 10, v250
	global_load_dwordx4 v[36:39], v36, s[98:99]
	s_waitcnt lgkmcnt(6)
	v_lshl_add_u32 v40, v40, 10, v250
	global_load_dwordx4 v[40:43], v40, s[98:99]
	s_waitcnt lgkmcnt(5)
	v_lshl_add_u32 v44, v44, 10, v250
	global_load_dwordx4 v[44:47], v44, s[98:99]
	s_waitcnt lgkmcnt(4)
	v_lshl_add_u32 v48, v48, 10, v250
	global_load_dwordx4 v[48:51], v48, s[98:99]
	s_waitcnt lgkmcnt(3)
	v_lshl_add_u32 v52, v52, 10, v250
	global_load_dwordx4 v[52:55], v52, s[98:99]
	s_waitcnt lgkmcnt(2)
	v_lshl_add_u32 v56, v56, 10, v250
	global_load_dwordx4 v[56:59], v56, s[98:99]
	s_waitcnt lgkmcnt(1)
	v_lshl_add_u32 v60, v60, 10, v250
	global_load_dwordx4 v[60:63], v60, s[98:99]
	s_waitcnt lgkmcnt(0)
	v_lshl_add_u32 v64, v64, 10, v250
	global_load_dwordx4 v[64:67], v64, s[98:99]
	s_branch .LBB0_826

; DI void up_issue(u32x4 (&W)[16], u32 (&pj)[16], const u32* pl, const unsigned char* wbase, int grp) {
; #pragma unroll
;   for (int j = 0; j < 16; ++j) {
;     pj[j] = pl[8 * j + grp];
;     W[j] = *(const u32x4*)(wbase + (size_t)(pj[j] >> 16) * 1024);
;   }
; }
; DI void peer_up_phase(const Params& p, unsigned char* smem, int layer, u32* ctr) {
;     ...
;       if (item >= 256) break;
;       const int t0 = item * 64 + 16 * w;
;       const unsigned char* wbase = wu + slice * 128 + c * 16;
;       {
;         const u32* src = hgp + (size_t)t0 * 128;
; #pragma unroll
;         for (int i = 0; i < 32; ++i) pl[i * 64 + lane] = src[i * 64 + lane];
;       }
;       float* ybase = yb + (size_t)t0 * 1024 + slice * 128;
;       u32x4 WA[16], WB[16];
;       u32 pA[16], pB[16];
;       up_issue(WA, pA, pl, wbase, grp);
.LBB0_1647:
	v_cmp_lt_i32_e32 vcc, s31, v4
	s_mov_b64 s[28:29], -1
	s_cbranch_vccnz .LBB0_1638
	s_waitcnt vmcnt(3)
	v_lshl_add_u32 v68, v4, 6, v3
	v_ashrrev_i32_e32 v69, 31, v68
	v_lshlrev_b64 v[4:5], 9, v[68:69]
	v_lshl_add_u64 v[4:5], s[16:17], 0, v[4:5]
	v_mov_b32_e32 v139, v133
	v_lshl_add_u64 v[6:7], v[4:5], 0, v[138:139]
	global_load_dword v38, v[6:7], off
	global_load_dword v39, v[6:7], off offset:256
	v_mov_b32_e32 v141, v133
	v_mov_b32_e32 v143, v133
	v_mov_b32_e32 v145, v133
	v_mov_b32_e32 v147, v133
	v_mov_b32_e32 v149, v133
	v_mov_b32_e32 v151, v133
	v_mov_b32_e32 v153, v133
	v_mov_b32_e32 v155, v133
	v_mov_b32_e32 v157, v133
	v_mov_b32_e32 v159, v133
	v_mov_b32_e32 v163, v133
	v_mov_b32_e32 v165, v133
	v_mov_b32_e32 v167, v133
	v_mov_b32_e32 v169, v133
	v_mov_b32_e32 v171, v133
	v_mov_b32_e32 v173, v133
	v_lshl_add_u64 v[8:9], v[4:5], 0, v[140:141]
	v_lshl_add_u64 v[10:11], v[4:5], 0, v[142:143]
	v_lshl_add_u64 v[12:13], v[4:5], 0, v[144:145]
	v_lshl_add_u64 v[14:15], v[4:5], 0, v[146:147]
	v_lshl_add_u64 v[16:17], v[4:5], 0, v[148:149]
	v_lshl_add_u64 v[18:19], v[4:5], 0, v[150:151]
	v_lshl_add_u64 v[20:21], v[4:5], 0, v[152:153]
	v_lshl_add_u64 v[22:23], v[4:5], 0, v[154:155]
	v_lshl_add_u64 v[24:25], v[4:5], 0, v[156:157]
	v_lshl_add_u64 v[26:27], v[4:5], 0, v[158:159]
	v_lshl_add_u64 v[28:29], v[4:5], 0, v[162:163]
	v_lshl_add_u64 v[30:31], v[4:5], 0, v[164:165]
	v_lshl_add_u64 v[32:33], v[4:5], 0, v[166:167]
	v_lshl_add_u64 v[34:35], v[4:5], 0, v[168:169]
	v_lshl_add_u64 v[36:37], v[4:5], 0, v[170:171]
	v_lshl_add_u64 v[4:5], v[4:5], 0, v[172:173]
	global_load_dword v70, v[6:7], off offset:512
	global_load_dword v71, v[6:7], off offset:768
	global_load_dword v72, v[6:7], off offset:1024
	global_load_dword v73, v[6:7], off offset:1280
	global_load_dword v74, v[6:7], off offset:1536
	global_load_dword v75, v[6:7], off offset:1792
	global_load_dword v76, v[6:7], off offset:2048
	global_load_dword v77, v[6:7], off offset:2304
	global_load_dword v78, v[6:7], off offset:2560
	global_load_dword v79, v[6:7], off offset:2816
	global_load_dword v80, v[6:7], off offset:3072
	global_load_dword v81, v[6:7], off offset:3328
	global_load_dword v82, v[6:7], off offset:3584
	global_load_dword v83, v[6:7], off offset:3840
	global_load_dword v84, v[8:9], off
	global_load_dword v85, v[10:11], off
	global_load_dword v86, v[12:13], off
	global_load_dword v87, v[14:15], off
	global_load_dword v88, v[16:17], off
	global_load_dword v89, v[18:19], off
	global_load_dword v90, v[20:21], off
	global_load_dword v91, v[22:23], off
	global_load_dword v92, v[24:25], off
	global_load_dword v93, v[26:27], off
	global_load_dword v94, v[28:29], off
	global_load_dword v95, v[30:31], off
	global_load_dword v96, v[32:33], off
	global_load_dword v97, v[34:35], off
	global_load_dword v98, v[36:37], off
	global_load_dword v99, v[4:5], off
	v_cmp_lt_i32_e32 vcc, v223, v218
	v_lshlrev_b64 v[68:69], 12, v[68:69]
	s_mov_b32 s36, 0
	v_lshl_add_u64 v[188:189], v[176:177], 0, v[68:69]
	v_mov_b32_e32 v145, v214
	s_waitcnt vmcnt(30)
	ds_write2st64_b32 v213, v38, v39 offset0:1 offset1:2
	ds_read2_b32 v[178:179], v212 offset0:64 offset1:72
	ds_read2_b32 v[180:181], v212 offset0:80 offset1:88
	ds_read2_b32 v[182:183], v212 offset0:96 offset1:104
	ds_read2_b32 v[184:185], v212 offset0:112 offset1:120
	ds_read2_b32 v[186:187], v212 offset0:128 offset1:136
	s_waitcnt lgkmcnt(4)
	v_lshlrev_b32_sdwa v132, v215, v178 dst_sel:DWORD dst_unused:UNUSED_PAD src0_sel:DWORD src1_sel:WORD_1
	v_add_u32_e32 v12, v250, v132
	v_lshlrev_b32_sdwa v132, v215, v179 dst_sel:DWORD dst_unused:UNUSED_PAD src0_sel:DWORD src1_sel:WORD_1
	v_add_u32_e32 v14, v250, v132
	s_waitcnt lgkmcnt(3)
	v_lshlrev_b32_sdwa v132, v215, v180 dst_sel:DWORD dst_unused:UNUSED_PAD src0_sel:DWORD src1_sel:WORD_1
	v_add_u32_e32 v20, v250, v132
	v_lshlrev_b32_sdwa v132, v215, v181 dst_sel:DWORD dst_unused:UNUSED_PAD src0_sel:DWORD src1_sel:WORD_1
	v_add_u32_e32 v22, v250, v132
	s_waitcnt lgkmcnt(2)
	v_lshlrev_b32_sdwa v132, v215, v182 dst_sel:DWORD dst_unused:UNUSED_PAD src0_sel:DWORD src1_sel:WORD_1
	v_add_u32_e32 v28, v250, v132
	v_lshlrev_b32_sdwa v132, v215, v183 dst_sel:DWORD dst_unused:UNUSED_PAD src0_sel:DWORD src1_sel:WORD_1
	v_add_u32_e32 v30, v250, v132
	s_waitcnt lgkmcnt(1)
	v_lshlrev_b32_sdwa v132, v215, v184 dst_sel:DWORD dst_unused:UNUSED_PAD src0_sel:DWORD src1_sel:WORD_1
	v_add_u32_e32 v36, v250, v132
	v_lshlrev_b32_sdwa v132, v215, v185 dst_sel:DWORD dst_unused:UNUSED_PAD src0_sel:DWORD src1_sel:WORD_1
	global_load_dwordx4 v[4:7], v12, s[98:99]
	global_load_dwordx4 v[8:11], v14, s[98:99]
	s_nop 0
	global_load_dwordx4 v[12:15], v20, s[98:99]
	global_load_dwordx4 v[16:19], v22, s[98:99]
	s_nop 0
	global_load_dwordx4 v[20:23], v28, s[98:99]
	global_load_dwordx4 v[24:27], v30, s[98:99]
	v_add_u32_e32 v38, v250, v132
	global_load_dwordx4 v[28:31], v36, s[98:99]
	global_load_dwordx4 v[32:35], v38, s[98:99]
	ds_read2_b32 v[190:191], v212 offset0:144 offset1:152
	s_waitcnt lgkmcnt(1)
	v_lshlrev_b32_sdwa v132, v215, v186 dst_sel:DWORD dst_unused:UNUSED_PAD src0_sel:DWORD src1_sel:WORD_1
	v_add_u32_e32 v36, v250, v132
	v_lshlrev_b32_sdwa v132, v215, v187 dst_sel:DWORD dst_unused:UNUSED_PAD src0_sel:DWORD src1_sel:WORD_1
	v_add_u32_e32 v40, v250, v132
	s_waitcnt lgkmcnt(0)
	v_lshlrev_b32_sdwa v132, v215, v190 dst_sel:DWORD dst_unused:UNUSED_PAD src0_sel:DWORD src1_sel:WORD_1
	global_load_dwordx4 v[36:39], v36, s[98:99]
	s_nop 0
	global_load_dwordx4 v[40:43], v40, s[98:99]
	v_add_u32_e32 v44, v250, v132
	ds_read2_b32 v[192:193], v212 offset0:160 offset1:168
	v_lshlrev_b32_sdwa v132, v215, v191 dst_sel:DWORD dst_unused:UNUSED_PAD src0_sel:DWORD src1_sel:WORD_1
	v_add_u32_e32 v48, v250, v132
	global_load_dwordx4 v[44:47], v44, s[98:99]
	s_nop 0
	global_load_dwordx4 v[48:51], v48, s[98:99]
	ds_read2_b32 v[194:195], v212 offset0:176 offset1:184
	s_waitcnt lgkmcnt(1)
; DI void up_issue(u32x4 (&W)[16], u32 (&pj)[16], const u32* pl, const unsigned char* wbase, int grp) {
; #pragma unroll
;   for (int j = 0; j < 16; ++j) {
;     pj[j] = pl[8 * j + grp];
;     W[j] = *(const u32x4*)(wbase + (size_t)(pj[j] >> 16) * 1024);
;   }
; }
; DI void up_math(const u32x4 (&W)[16], const u32 (&pj)[16], float* __restrict__ yrow, int lane) {
;   f2 y[8];
; #pragma unroll
; DI void peer_up_phase(const Params& p, unsigned char* smem, int layer, u32* ctr) {
;   unsigned char* ws = p.ws;
;   const u32* hgp = (const u32*)(ws + OFF_HGP);
;   const unsigned char* wu = ws + OFF_WUP + (size_t)layer * 16384 * 1024;
;   float* yb = (float*)(ws + OFF_YB);
;   int* slot = (int*)smem;
;   const int tid = opaque_tid(), lane = tid & 63, w = tid >> 6;
;   const int grp = lane >> 3, c = lane & 7;
;   u32* pl = (u32*)(smem + 256) + w * 2048;
;   const int xcc = (int)xcc_id();
;   xcc_census(ws, ctr + 8, slot + 4, tid);
;   const bool stat = (slot[7] == 8);
;   int it_next = slot[4];
;   const int it_step = slot[5], xi = slot[6];
;   for (int si = 0; si < (stat ? 1 : 8); ++si) {
;     const int slice = stat ? xi : ((xcc + si) & 7);
;     for (;;) {
;       int item;
;       if (stat) { item = it_next; it_next += it_step; }
;       else {
;         __syncthreads();
;         if (tid == 0) *slot = (int)atomicAdd(ctr + slice, 1u);
;         __syncthreads();
;         item = *slot;
;       }
;       if (item >= 256) break;
;       const int t0 = item * 64 + 16 * w;
;       const unsigned char* wbase = wu + slice * 128 + c * 16;
;       {
;         const u32* src = hgp + (size_t)t0 * 128;
; #pragma unroll
;         for (int i = 0; i < 32; ++i) pl[i * 64 + lane] = src[i * 64 + lane];
;       }
;       float* ybase = yb + (size_t)t0 * 1024 + slice * 128;
;       u32x4 WA[16], WB[16];
;       u32 pA[16], pB[16];
;       up_issue(WA, pA, pl, wbase, grp);
;       for (int tl = 0; tl < 16; tl += 2) {
;         up_issue(WB, pB, pl + (tl + 1) * 128, wbase, grp);
;         __builtin_amdgcn_sched_barrier(0);
;         up_math(WA, pA, ybase + (size_t)tl * 1024, lane);
;         __builtin_amdgcn_sched_barrier(0);
;         if (tl + 2 < 16) up_issue(WA, pA, pl + (tl + 2) * 128, wbase, grp);
;         __builtin_amdgcn_sched_barrier(0);
;         up_math(WB, pB, ybase + (size_t)(tl + 1) * 1024, lane);
;         __builtin_amdgcn_sched_barrier(0);
;       }
	v_lshlrev_b32_sdwa v132, v215, v192 dst_sel:DWORD dst_unused:UNUSED_PAD src0_sel:DWORD src1_sel:WORD_1
	v_add_u32_e32 v52, v250, v132
	v_lshlrev_b32_sdwa v132, v215, v193 dst_sel:DWORD dst_unused:UNUSED_PAD src0_sel:DWORD src1_sel:WORD_1
	v_add_u32_e32 v56, v250, v132
	s_waitcnt lgkmcnt(0)
	v_lshlrev_b32_sdwa v132, v215, v194 dst_sel:DWORD dst_unused:UNUSED_PAD src0_sel:DWORD src1_sel:WORD_1
	v_add_u32_e32 v60, v250, v132
	v_lshlrev_b32_sdwa v132, v215, v195 dst_sel:DWORD dst_unused:UNUSED_PAD src0_sel:DWORD src1_sel:WORD_1
	v_add_u32_e32 v64, v250, v132
	global_load_dwordx4 v[52:55], v52, s[98:99]
	s_nop 0
	global_load_dwordx4 v[56:59], v56, s[98:99]
	s_nop 0
	global_load_dwordx4 v[60:63], v60, s[98:99]
	s_nop 0
	global_load_dwordx4 v[64:67], v64, s[98:99]
	s_waitcnt vmcnt(44)
	ds_write2st64_b32 v213, v70, v71 offset0:3 offset1:4
	s_waitcnt vmcnt(42)
	ds_write2st64_b32 v213, v72, v73 offset0:5 offset1:6
	s_waitcnt vmcnt(40)
	ds_write2st64_b32 v213, v74, v75 offset0:7 offset1:8
	s_waitcnt vmcnt(38)
	ds_write2st64_b32 v213, v76, v77 offset0:9 offset1:10
	s_waitcnt vmcnt(36)
	ds_write2st64_b32 v213, v78, v79 offset0:11 offset1:12
	s_waitcnt vmcnt(34)
	ds_write2st64_b32 v213, v80, v81 offset0:13 offset1:14
	s_waitcnt vmcnt(32)
	ds_write2st64_b32 v213, v82, v83 offset0:15 offset1:16
	s_waitcnt vmcnt(30)
	ds_write2st64_b32 v213, v84, v85 offset0:17 offset1:18
	s_waitcnt vmcnt(28)
	ds_write2st64_b32 v213, v86, v87 offset0:19 offset1:20
	s_waitcnt vmcnt(26)
	ds_write2st64_b32 v213, v88, v89 offset0:21 offset1:22
	s_waitcnt vmcnt(24)
	ds_write2st64_b32 v213, v90, v91 offset0:23 offset1:24
	s_waitcnt vmcnt(22)
	ds_write2st64_b32 v213, v92, v93 offset0:25 offset1:26
	s_waitcnt vmcnt(20)
	ds_write2st64_b32 v213, v94, v95 offset0:27 offset1:28
	s_waitcnt vmcnt(18)
	ds_write2st64_b32 v213, v96, v97 offset0:29 offset1:30
	s_waitcnt vmcnt(16)
	ds_write2st64_b32 v213, v98, v99 offset0:31 offset1:32
	v_cndmask_b32_e32 v70, v161, v223, vcc
	v_cmp_lt_i32_e32 vcc, v224, v218
	v_lshlrev_b32_e32 v139, 2, v70
	s_nop 0
	v_cndmask_b32_e32 v70, v161, v224, vcc
	v_cmp_lt_i32_e32 vcc, v222, v218
	v_lshlrev_b32_e32 v141, 2, v70
	s_nop 0
	v_cndmask_b32_e32 v70, v161, v222, vcc
	v_lshlrev_b32_e32 v143, 2, v70
	v_lshlrev_b32_e32 v178, 16, v178
	v_lshlrev_b32_e32 v179, 16, v179
	v_lshlrev_b32_e32 v180, 16, v180
	v_lshlrev_b32_e32 v181, 16, v181
	v_lshlrev_b32_e32 v182, 16, v182
	v_lshlrev_b32_e32 v183, 16, v183
	v_lshlrev_b32_e32 v184, 16, v184
	v_lshlrev_b32_e32 v185, 16, v185
	v_lshlrev_b32_e32 v186, 16, v186
	v_lshlrev_b32_e32 v187, 16, v187
	v_lshlrev_b32_e32 v190, 16, v190
	v_lshlrev_b32_e32 v191, 16, v191
	v_lshlrev_b32_e32 v192, 16, v192
	v_lshlrev_b32_e32 v193, 16, v193
	v_lshlrev_b32_e32 v194, 16, v194
	v_lshlrev_b32_e32 v195, 16, v195
	v_mov_b32_e32 v210, 0
	v_mov_b32_e32 v211, 0
	v_mov_b32_e32 v208, 0
	v_mov_b32_e32 v209, 0
	v_mov_b32_e32 v206, 0
	v_mov_b32_e32 v207, 0
	v_mov_b32_e32 v204, 0
	v_mov_b32_e32 v205, 0
	v_mov_b32_e32 v202, 0
	v_mov_b32_e32 v203, 0
	v_mov_b32_e32 v200, 0
	v_mov_b32_e32 v201, 0
	v_mov_b32_e32 v198, 0
	v_mov_b32_e32 v199, 0
	v_mov_b32_e32 v196, 0
	v_mov_b32_e32 v197, 0
	s_branch .LBB0_1650
.LBB0_1649:
	s_add_i32 s36, s36, 2
	s_waitcnt vmcnt(16)
	v_cvt_pk_f32_fp8_e32 v[216:217], v128
	v_cvt_pk_f32_fp8_sdwa v[226:227], v128 src0_sel:WORD_1
	v_cvt_pk_f32_fp8_e32 v[228:229], v129
	v_cvt_pk_f32_fp8_sdwa v[128:129], v129 src0_sel:WORD_1
	v_cvt_pk_f32_fp8_e32 v[230:231], v130
	v_cvt_pk_f32_fp8_sdwa v[232:233], v130 src0_sel:WORD_1
	v_cvt_pk_f32_fp8_e32 v[234:235], v131
	v_cvt_pk_f32_fp8_sdwa v[130:131], v131 src0_sel:WORD_1
	v_pk_fma_f32 v[216:217], v[210:211], v[216:217], 0 op_sel_hi:[0,1,0]
	v_pk_fma_f32 v[226:227], v[210:211], v[226:227], 0 op_sel_hi:[0,1,0]
	v_pk_fma_f32 v[228:229], v[210:211], v[228:229], 0 op_sel_hi:[0,1,0]
	v_pk_fma_f32 v[128:129], v[210:211], v[128:129], 0 op_sel_hi:[0,1,0]
	v_pk_fma_f32 v[230:231], v[210:211], v[230:231], 0 op_sel_hi:[0,1,0]
	v_pk_fma_f32 v[232:233], v[210:211], v[232:233], 0 op_sel_hi:[0,1,0]
	v_pk_fma_f32 v[234:235], v[210:211], v[234:235], 0 op_sel_hi:[0,1,0]
	v_pk_fma_f32 v[130:131], v[210:211], v[130:131], 0 op_sel_hi:[0,1,0]
	v_mov_b32_e32 v132, v211
	s_waitcnt vmcnt(15)
	v_cvt_pk_f32_fp8_e32 v[210:211], v124
	v_cvt_pk_f32_fp8_sdwa v[236:237], v124 src0_sel:WORD_1
	v_cvt_pk_f32_fp8_e32 v[238:239], v125
	v_cvt_pk_f32_fp8_sdwa v[124:125], v125 src0_sel:WORD_1
	v_pk_fma_f32 v[210:211], v[132:133], v[210:211], v[216:217] op_sel_hi:[0,1,1]
	v_pk_fma_f32 v[216:217], v[132:133], v[236:237], v[226:227] op_sel_hi:[0,1,1]
	v_pk_fma_f32 v[226:227], v[132:133], v[238:239], v[228:229] op_sel_hi:[0,1,1]
	v_pk_fma_f32 v[124:125], v[132:133], v[124:125], v[128:129] op_sel_hi:[0,1,1]
	v_cvt_pk_f32_fp8_e32 v[128:129], v126
	v_cvt_pk_f32_fp8_sdwa v[228:229], v126 src0_sel:WORD_1
	v_cvt_pk_f32_fp8_e32 v[236:237], v127
	v_cvt_pk_f32_fp8_sdwa v[126:127], v127 src0_sel:WORD_1
	v_pk_fma_f32 v[128:129], v[132:133], v[128:129], v[230:231] op_sel_hi:[0,1,1]
	v_pk_fma_f32 v[228:229], v[132:133], v[228:229], v[232:233] op_sel_hi:[0,1,1]
	v_pk_fma_f32 v[230:231], v[132:133], v[236:237], v[234:235] op_sel_hi:[0,1,1]
	s_waitcnt vmcnt(14)
; DI void up_math(const u32x4 (&W)[16], const u32 (&pj)[16], float* __restrict__ yrow, int lane) {
;     ...
; #pragma unroll
;   for (int j = 0; j < 16; ++j) {
;     const float h = __uint_as_float(pj[j] << 16);
;     const f2 hh = {h, h};
; #pragma unroll
;     for (int d = 0; d < 4; ++d) {
;       f2 lo = __builtin_amdgcn_cvt_pk_f32_fp8((int)W[j][d], false);
;       f2 hi = __builtin_amdgcn_cvt_pk_f32_fp8((int)W[j][d], true);
;       y[2 * d] = lo * hh + y[2 * d];
;       y[2 * d + 1] = hi * hh + y[2 * d + 1];
;     }
;   }
	v_cvt_pk_f32_fp8_e32 v[232:233], v120
	v_cvt_pk_f32_fp8_sdwa v[234:235], v120 src0_sel:WORD_1
	v_cvt_pk_f32_fp8_e32 v[236:237], v121
	v_cvt_pk_f32_fp8_sdwa v[120:121], v121 src0_sel:WORD_1
	v_pk_fma_f32 v[126:127], v[132:133], v[126:127], v[130:131] op_sel_hi:[0,1,1]
	v_pk_fma_f32 v[210:211], v[208:209], v[232:233], v[210:211] op_sel_hi:[0,1,1]
	v_pk_fma_f32 v[216:217], v[208:209], v[234:235], v[216:217] op_sel_hi:[0,1,1]
	v_pk_fma_f32 v[120:121], v[208:209], v[120:121], v[124:125] op_sel_hi:[0,1,1]
	v_cvt_pk_f32_fp8_e32 v[124:125], v122
	v_cvt_pk_f32_fp8_sdwa v[232:233], v122 src0_sel:WORD_1
	v_cvt_pk_f32_fp8_e32 v[234:235], v123
	v_cvt_pk_f32_fp8_sdwa v[122:123], v123 src0_sel:WORD_1
	v_pk_fma_f32 v[226:227], v[208:209], v[236:237], v[226:227] op_sel_hi:[0,1,1]
	v_pk_fma_f32 v[124:125], v[208:209], v[124:125], v[128:129] op_sel_hi:[0,1,1]
	v_pk_fma_f32 v[128:129], v[208:209], v[232:233], v[228:229] op_sel_hi:[0,1,1]
	v_pk_fma_f32 v[228:229], v[208:209], v[234:235], v[230:231] op_sel_hi:[0,1,1]
	v_pk_fma_f32 v[122:123], v[208:209], v[122:123], v[126:127] op_sel_hi:[0,1,1]
	v_mov_b32_e32 v126, v209
	s_waitcnt vmcnt(13)
	v_cvt_pk_f32_fp8_e32 v[130:131], v116
	v_cvt_pk_f32_fp8_sdwa v[208:209], v116 src0_sel:WORD_1
	v_cvt_pk_f32_fp8_e32 v[230:231], v117
	v_cvt_pk_f32_fp8_sdwa v[116:117], v117 src0_sel:WORD_1
	v_pk_fma_f32 v[130:131], v[126:127], v[130:131], v[210:211] op_sel_hi:[0,1,1]
	v_pk_fma_f32 v[208:209], v[126:127], v[208:209], v[216:217] op_sel_hi:[0,1,1]
	v_pk_fma_f32 v[210:211], v[126:127], v[230:231], v[226:227] op_sel_hi:[0,1,1]
	v_pk_fma_f32 v[116:117], v[126:127], v[116:117], v[120:121] op_sel_hi:[0,1,1]
	v_cvt_pk_f32_fp8_e32 v[120:121], v118
	v_cvt_pk_f32_fp8_sdwa v[216:217], v118 src0_sel:WORD_1
	v_cvt_pk_f32_fp8_e32 v[226:227], v119
	v_cvt_pk_f32_fp8_sdwa v[118:119], v119 src0_sel:WORD_1
	v_pk_fma_f32 v[120:121], v[126:127], v[120:121], v[124:125] op_sel_hi:[0,1,1]
	v_pk_fma_f32 v[124:125], v[126:127], v[216:217], v[128:129] op_sel_hi:[0,1,1]
	v_pk_fma_f32 v[128:129], v[126:127], v[226:227], v[228:229] op_sel_hi:[0,1,1]
	v_pk_fma_f32 v[118:119], v[126:127], v[118:119], v[122:123] op_sel_hi:[0,1,1]
	s_waitcnt vmcnt(12)
	v_cvt_pk_f32_fp8_e32 v[126:127], v112
	v_cvt_pk_f32_fp8_sdwa v[216:217], v112 src0_sel:WORD_1
	v_cvt_pk_f32_fp8_e32 v[226:227], v113
	v_cvt_pk_f32_fp8_sdwa v[112:113], v113 src0_sel:WORD_1
	v_pk_fma_f32 v[126:127], v[206:207], v[126:127], v[130:131] op_sel_hi:[0,1,1]
	v_pk_fma_f32 v[130:131], v[206:207], v[216:217], v[208:209] op_sel_hi:[0,1,1]
	v_pk_fma_f32 v[208:209], v[206:207], v[226:227], v[210:211] op_sel_hi:[0,1,1]
	v_pk_fma_f32 v[112:113], v[206:207], v[112:113], v[116:117] op_sel_hi:[0,1,1]
	v_cvt_pk_f32_fp8_e32 v[116:117], v114
	v_cvt_pk_f32_fp8_sdwa v[210:211], v114 src0_sel:WORD_1
	v_cvt_pk_f32_fp8_e32 v[216:217], v115
	v_cvt_pk_f32_fp8_sdwa v[114:115], v115 src0_sel:WORD_1
	v_pk_fma_f32 v[116:117], v[206:207], v[116:117], v[120:121] op_sel_hi:[0,1,1]
	v_pk_fma_f32 v[120:121], v[206:207], v[210:211], v[124:125] op_sel_hi:[0,1,1]
	v_pk_fma_f32 v[124:125], v[206:207], v[216:217], v[128:129] op_sel_hi:[0,1,1]
	v_pk_fma_f32 v[114:115], v[206:207], v[114:115], v[118:119] op_sel_hi:[0,1,1]
	v_mov_b32_e32 v118, v207
	s_waitcnt vmcnt(11)
	v_cvt_pk_f32_fp8_e32 v[122:123], v108
	v_cvt_pk_f32_fp8_sdwa v[128:129], v108 src0_sel:WORD_1
	v_cvt_pk_f32_fp8_e32 v[206:207], v109
	v_cvt_pk_f32_fp8_sdwa v[108:109], v109 src0_sel:WORD_1
	v_pk_fma_f32 v[122:123], v[118:119], v[122:123], v[126:127] op_sel_hi:[0,1,1]
	v_pk_fma_f32 v[126:127], v[118:119], v[128:129], v[130:131] op_sel_hi:[0,1,1]
	v_pk_fma_f32 v[128:129], v[118:119], v[206:207], v[208:209] op_sel_hi:[0,1,1]
	v_pk_fma_f32 v[108:109], v[118:119], v[108:109], v[112:113] op_sel_hi:[0,1,1]
	v_cvt_pk_f32_fp8_e32 v[112:113], v110
	v_cvt_pk_f32_fp8_sdwa v[130:131], v110 src0_sel:WORD_1
	v_cvt_pk_f32_fp8_e32 v[206:207], v111
	v_cvt_pk_f32_fp8_sdwa v[110:111], v111 src0_sel:WORD_1
	v_pk_fma_f32 v[112:113], v[118:119], v[112:113], v[116:117] op_sel_hi:[0,1,1]
	v_pk_fma_f32 v[116:117], v[118:119], v[130:131], v[120:121] op_sel_hi:[0,1,1]
	v_pk_fma_f32 v[120:121], v[118:119], v[206:207], v[124:125] op_sel_hi:[0,1,1]
	v_pk_fma_f32 v[110:111], v[118:119], v[110:111], v[114:115] op_sel_hi:[0,1,1]
	s_waitcnt vmcnt(10)
	v_cvt_pk_f32_fp8_e32 v[118:119], v104
	v_cvt_pk_f32_fp8_sdwa v[124:125], v104 src0_sel:WORD_1
	v_cvt_pk_f32_fp8_e32 v[130:131], v105
	v_cvt_pk_f32_fp8_sdwa v[104:105], v105 src0_sel:WORD_1
	v_pk_fma_f32 v[118:119], v[204:205], v[118:119], v[122:123] op_sel_hi:[0,1,1]
	v_pk_fma_f32 v[122:123], v[204:205], v[124:125], v[126:127] op_sel_hi:[0,1,1]
	v_pk_fma_f32 v[124:125], v[204:205], v[130:131], v[128:129] op_sel_hi:[0,1,1]
	v_pk_fma_f32 v[104:105], v[204:205], v[104:105], v[108:109] op_sel_hi:[0,1,1]
	v_cvt_pk_f32_fp8_e32 v[108:109], v106
	v_cvt_pk_f32_fp8_sdwa v[126:127], v106 src0_sel:WORD_1
	v_cvt_pk_f32_fp8_e32 v[128:129], v107
	v_cvt_pk_f32_fp8_sdwa v[106:107], v107 src0_sel:WORD_1
	v_pk_fma_f32 v[108:109], v[204:205], v[108:109], v[112:113] op_sel_hi:[0,1,1]
	v_pk_fma_f32 v[112:113], v[204:205], v[126:127], v[116:117] op_sel_hi:[0,1,1]
	v_pk_fma_f32 v[116:117], v[204:205], v[128:129], v[120:121] op_sel_hi:[0,1,1]
	v_pk_fma_f32 v[106:107], v[204:205], v[106:107], v[110:111] op_sel_hi:[0,1,1]
	s_waitcnt vmcnt(9)
; DI void up_math(const u32x4 (&W)[16], const u32 (&pj)[16], float* __restrict__ yrow, int lane) {
;     ...
; #pragma unroll
;   for (int j = 0; j < 16; ++j) {
;     const float h = __uint_as_float(pj[j] << 16);
;     const f2 hh = {h, h};
; #pragma unroll
;     for (int d = 0; d < 4; ++d) {
;       f2 lo = __builtin_amdgcn_cvt_pk_f32_fp8((int)W[j][d], false);
;       f2 hi = __builtin_amdgcn_cvt_pk_f32_fp8((int)W[j][d], true);
;       y[2 * d] = lo * hh + y[2 * d];
;       y[2 * d + 1] = hi * hh + y[2 * d + 1];
;     }
;   }
	v_cvt_pk_f32_fp8_e32 v[114:115], v100
	v_cvt_pk_f32_fp8_sdwa v[120:121], v100 src0_sel:WORD_1
	v_cvt_pk_f32_fp8_e32 v[126:127], v101
	v_cvt_pk_f32_fp8_sdwa v[100:101], v101 src0_sel:WORD_1
	v_pk_fma_f32 v[114:115], v[204:205], v[114:115], v[118:119] op_sel:[1,0,0] op_sel_hi:[1,1,1]
	v_pk_fma_f32 v[118:119], v[204:205], v[120:121], v[122:123] op_sel:[1,0,0] op_sel_hi:[1,1,1]
	v_pk_fma_f32 v[120:121], v[204:205], v[126:127], v[124:125] op_sel:[1,0,0] op_sel_hi:[1,1,1]
	v_pk_fma_f32 v[100:101], v[204:205], v[100:101], v[104:105] op_sel:[1,0,0] op_sel_hi:[1,1,1]
	v_cvt_pk_f32_fp8_e32 v[104:105], v102
	v_cvt_pk_f32_fp8_sdwa v[122:123], v102 src0_sel:WORD_1
	v_cvt_pk_f32_fp8_e32 v[124:125], v103
	v_cvt_pk_f32_fp8_sdwa v[102:103], v103 src0_sel:WORD_1
	v_pk_fma_f32 v[104:105], v[204:205], v[104:105], v[108:109] op_sel:[1,0,0] op_sel_hi:[1,1,1]
	v_pk_fma_f32 v[108:109], v[204:205], v[122:123], v[112:113] op_sel:[1,0,0] op_sel_hi:[1,1,1]
	v_pk_fma_f32 v[112:113], v[204:205], v[124:125], v[116:117] op_sel:[1,0,0] op_sel_hi:[1,1,1]
	v_pk_fma_f32 v[102:103], v[204:205], v[102:103], v[106:107] op_sel:[1,0,0] op_sel_hi:[1,1,1]
	s_waitcnt vmcnt(8)
	v_cvt_pk_f32_fp8_e32 v[110:111], v96
	v_cvt_pk_f32_fp8_sdwa v[116:117], v96 src0_sel:WORD_1
	v_cvt_pk_f32_fp8_e32 v[122:123], v97
	v_cvt_pk_f32_fp8_sdwa v[96:97], v97 src0_sel:WORD_1
	v_pk_fma_f32 v[110:111], v[202:203], v[110:111], v[114:115] op_sel_hi:[0,1,1]
	v_pk_fma_f32 v[114:115], v[202:203], v[116:117], v[118:119] op_sel_hi:[0,1,1]
	v_pk_fma_f32 v[116:117], v[202:203], v[122:123], v[120:121] op_sel_hi:[0,1,1]
	v_pk_fma_f32 v[96:97], v[202:203], v[96:97], v[100:101] op_sel_hi:[0,1,1]
	v_cvt_pk_f32_fp8_e32 v[100:101], v98
	v_cvt_pk_f32_fp8_sdwa v[118:119], v98 src0_sel:WORD_1
	v_cvt_pk_f32_fp8_e32 v[120:121], v99
	v_cvt_pk_f32_fp8_sdwa v[98:99], v99 src0_sel:WORD_1
	v_pk_fma_f32 v[100:101], v[202:203], v[100:101], v[104:105] op_sel_hi:[0,1,1]
	v_pk_fma_f32 v[104:105], v[202:203], v[118:119], v[108:109] op_sel_hi:[0,1,1]
	v_pk_fma_f32 v[108:109], v[202:203], v[120:121], v[112:113] op_sel_hi:[0,1,1]
	v_pk_fma_f32 v[98:99], v[202:203], v[98:99], v[102:103] op_sel_hi:[0,1,1]
	s_waitcnt vmcnt(7)
	v_cvt_pk_f32_fp8_e32 v[106:107], v92
	v_cvt_pk_f32_fp8_sdwa v[112:113], v92 src0_sel:WORD_1
	v_cvt_pk_f32_fp8_e32 v[118:119], v93
	v_cvt_pk_f32_fp8_sdwa v[92:93], v93 src0_sel:WORD_1
	v_pk_fma_f32 v[106:107], v[202:203], v[106:107], v[110:111] op_sel:[1,0,0] op_sel_hi:[1,1,1]
	v_pk_fma_f32 v[110:111], v[202:203], v[112:113], v[114:115] op_sel:[1,0,0] op_sel_hi:[1,1,1]
	v_pk_fma_f32 v[112:113], v[202:203], v[118:119], v[116:117] op_sel:[1,0,0] op_sel_hi:[1,1,1]
	v_pk_fma_f32 v[92:93], v[202:203], v[92:93], v[96:97] op_sel:[1,0,0] op_sel_hi:[1,1,1]
	v_cvt_pk_f32_fp8_e32 v[96:97], v94
	v_cvt_pk_f32_fp8_sdwa v[114:115], v94 src0_sel:WORD_1
	v_cvt_pk_f32_fp8_e32 v[116:117], v95
	v_cvt_pk_f32_fp8_sdwa v[94:95], v95 src0_sel:WORD_1
	v_pk_fma_f32 v[96:97], v[202:203], v[96:97], v[100:101] op_sel:[1,0,0] op_sel_hi:[1,1,1]
	v_pk_fma_f32 v[100:101], v[202:203], v[114:115], v[104:105] op_sel:[1,0,0] op_sel_hi:[1,1,1]
	v_pk_fma_f32 v[104:105], v[202:203], v[116:117], v[108:109] op_sel:[1,0,0] op_sel_hi:[1,1,1]
	v_pk_fma_f32 v[94:95], v[202:203], v[94:95], v[98:99] op_sel:[1,0,0] op_sel_hi:[1,1,1]
	s_waitcnt vmcnt(6)
	v_cvt_pk_f32_fp8_e32 v[102:103], v88
	v_cvt_pk_f32_fp8_sdwa v[108:109], v88 src0_sel:WORD_1
	v_cvt_pk_f32_fp8_e32 v[114:115], v89
	v_cvt_pk_f32_fp8_sdwa v[88:89], v89 src0_sel:WORD_1
	v_pk_fma_f32 v[102:103], v[200:201], v[102:103], v[106:107] op_sel_hi:[0,1,1]
	v_pk_fma_f32 v[106:107], v[200:201], v[108:109], v[110:111] op_sel_hi:[0,1,1]
	v_pk_fma_f32 v[108:109], v[200:201], v[114:115], v[112:113] op_sel_hi:[0,1,1]
	v_pk_fma_f32 v[88:89], v[200:201], v[88:89], v[92:93] op_sel_hi:[0,1,1]
	v_cvt_pk_f32_fp8_e32 v[92:93], v90
	v_cvt_pk_f32_fp8_sdwa v[110:111], v90 src0_sel:WORD_1
	v_cvt_pk_f32_fp8_e32 v[112:113], v91
	v_cvt_pk_f32_fp8_sdwa v[90:91], v91 src0_sel:WORD_1
	v_pk_fma_f32 v[92:93], v[200:201], v[92:93], v[96:97] op_sel_hi:[0,1,1]
	v_pk_fma_f32 v[96:97], v[200:201], v[110:111], v[100:101] op_sel_hi:[0,1,1]
	v_pk_fma_f32 v[100:101], v[200:201], v[112:113], v[104:105] op_sel_hi:[0,1,1]
	v_pk_fma_f32 v[90:91], v[200:201], v[90:91], v[94:95] op_sel_hi:[0,1,1]
	s_waitcnt vmcnt(5)
	v_cvt_pk_f32_fp8_e32 v[98:99], v84
	v_cvt_pk_f32_fp8_sdwa v[104:105], v84 src0_sel:WORD_1
	v_cvt_pk_f32_fp8_e32 v[110:111], v85
	v_cvt_pk_f32_fp8_sdwa v[84:85], v85 src0_sel:WORD_1
	v_pk_fma_f32 v[98:99], v[200:201], v[98:99], v[102:103] op_sel:[1,0,0] op_sel_hi:[1,1,1]
	v_pk_fma_f32 v[102:103], v[200:201], v[104:105], v[106:107] op_sel:[1,0,0] op_sel_hi:[1,1,1]
	v_pk_fma_f32 v[104:105], v[200:201], v[110:111], v[108:109] op_sel:[1,0,0] op_sel_hi:[1,1,1]
	v_pk_fma_f32 v[84:85], v[200:201], v[84:85], v[88:89] op_sel:[1,0,0] op_sel_hi:[1,1,1]
	v_cvt_pk_f32_fp8_e32 v[88:89], v86
	v_cvt_pk_f32_fp8_sdwa v[106:107], v86 src0_sel:WORD_1
	v_cvt_pk_f32_fp8_e32 v[108:109], v87
	v_cvt_pk_f32_fp8_sdwa v[86:87], v87 src0_sel:WORD_1
	v_pk_fma_f32 v[88:89], v[200:201], v[88:89], v[92:93] op_sel:[1,0,0] op_sel_hi:[1,1,1]
	v_pk_fma_f32 v[92:93], v[200:201], v[106:107], v[96:97] op_sel:[1,0,0] op_sel_hi:[1,1,1]
	v_pk_fma_f32 v[96:97], v[200:201], v[108:109], v[100:101] op_sel:[1,0,0] op_sel_hi:[1,1,1]
	v_pk_fma_f32 v[86:87], v[200:201], v[86:87], v[90:91] op_sel:[1,0,0] op_sel_hi:[1,1,1]
	s_waitcnt vmcnt(4)
; DI void up_math(const u32x4 (&W)[16], const u32 (&pj)[16], float* __restrict__ yrow, int lane) {
;     ...
; #pragma unroll
;   for (int j = 0; j < 16; ++j) {
;     const float h = __uint_as_float(pj[j] << 16);
;     const f2 hh = {h, h};
; #pragma unroll
;     for (int d = 0; d < 4; ++d) {
;       f2 lo = __builtin_amdgcn_cvt_pk_f32_fp8((int)W[j][d], false);
;       f2 hi = __builtin_amdgcn_cvt_pk_f32_fp8((int)W[j][d], true);
;       y[2 * d] = lo * hh + y[2 * d];
;       y[2 * d + 1] = hi * hh + y[2 * d + 1];
;     }
;   }
;   const bool b5 = lane & 32, b4 = lane & 16, b3 = lane & 8;
;   f2 q4[4];
; #pragma unroll
;   for (int i = 0; i < 4; ++i) {
;     f2 snd = b5 ? y[i] : y[i + 4]; f2 kp = b5 ? y[i + 4] : y[i];
;     q4[i] = f2{kp.x + __shfl_xor(snd.x, 32), kp.y + __shfl_xor(snd.y, 32)};
;   }
;   f2 r2[2];
; #pragma unroll
;   for (int i = 0; i < 2; ++i) {
;     f2 snd = b4 ? q4[i] : q4[i + 2]; f2 kp = b4 ? q4[i + 2] : q4[i];
;     r2[i] = f2{kp.x + __shfl_xor(snd.x, 16), kp.y + __shfl_xor(snd.y, 16)};
;   }
;   f2 a;
;   { f2 snd = b3 ? r2[0] : r2[1]; f2 kp = b3 ? r2[1] : r2[0]; a = f2{kp.x + __shfl_xor(snd.x, 8), kp.y + __shfl_xor(snd.y, 8)}; }
;   const int ci = (b5 ? 4 : 0) + (b4 ? 2 : 0) + (b3 ? 1 : 0);
;   *(float2*)(yrow + (lane & 7) * 16 + 2 * ci) = make_float2(a.x, a.y);
; }
; DI void peer_up_phase(const Params& p, unsigned char* smem, int layer, u32* ctr) {
;     ...
;       for (int tl = 0; tl < 16; tl += 2) {
;         up_issue(WB, pB, pl + (tl + 1) * 128, wbase, grp);
;         __builtin_amdgcn_sched_barrier(0);
;         up_math(WA, pA, ybase + (size_t)tl * 1024, lane);
;         __builtin_amdgcn_sched_barrier(0);
;         if (tl + 2 < 16) up_issue(WA, pA, pl + (tl + 2) * 128, wbase, grp);
;         __builtin_amdgcn_sched_barrier(0);
;         up_math(WB, pB, ybase + (size_t)(tl + 1) * 1024, lane);
;         __builtin_amdgcn_sched_barrier(0);
;       }
	v_cvt_pk_f32_fp8_e32 v[94:95], v80
	v_cvt_pk_f32_fp8_sdwa v[100:101], v80 src0_sel:WORD_1
	v_cvt_pk_f32_fp8_e32 v[106:107], v81
	v_cvt_pk_f32_fp8_sdwa v[80:81], v81 src0_sel:WORD_1
	v_pk_fma_f32 v[94:95], v[198:199], v[94:95], v[98:99] op_sel_hi:[0,1,1]
	v_pk_fma_f32 v[98:99], v[198:199], v[100:101], v[102:103] op_sel_hi:[0,1,1]
	v_pk_fma_f32 v[100:101], v[198:199], v[106:107], v[104:105] op_sel_hi:[0,1,1]
	v_pk_fma_f32 v[80:81], v[198:199], v[80:81], v[84:85] op_sel_hi:[0,1,1]
	v_cvt_pk_f32_fp8_e32 v[84:85], v82
	v_cvt_pk_f32_fp8_sdwa v[102:103], v82 src0_sel:WORD_1
	v_cvt_pk_f32_fp8_e32 v[104:105], v83
	v_cvt_pk_f32_fp8_sdwa v[82:83], v83 src0_sel:WORD_1
	v_pk_fma_f32 v[84:85], v[198:199], v[84:85], v[88:89] op_sel_hi:[0,1,1]
	v_pk_fma_f32 v[88:89], v[198:199], v[102:103], v[92:93] op_sel_hi:[0,1,1]
	v_pk_fma_f32 v[92:93], v[198:199], v[104:105], v[96:97] op_sel_hi:[0,1,1]
	v_pk_fma_f32 v[82:83], v[198:199], v[82:83], v[86:87] op_sel_hi:[0,1,1]
	s_waitcnt vmcnt(3)
	v_cvt_pk_f32_fp8_e32 v[90:91], v76
	v_cvt_pk_f32_fp8_sdwa v[96:97], v76 src0_sel:WORD_1
	v_cvt_pk_f32_fp8_e32 v[102:103], v77
	v_cvt_pk_f32_fp8_sdwa v[76:77], v77 src0_sel:WORD_1
	v_pk_fma_f32 v[90:91], v[198:199], v[90:91], v[94:95] op_sel:[1,0,0] op_sel_hi:[1,1,1]
	v_pk_fma_f32 v[94:95], v[198:199], v[96:97], v[98:99] op_sel:[1,0,0] op_sel_hi:[1,1,1]
	v_pk_fma_f32 v[96:97], v[198:199], v[102:103], v[100:101] op_sel:[1,0,0] op_sel_hi:[1,1,1]
	v_pk_fma_f32 v[76:77], v[198:199], v[76:77], v[80:81] op_sel:[1,0,0] op_sel_hi:[1,1,1]
	v_cvt_pk_f32_fp8_e32 v[80:81], v78
	v_cvt_pk_f32_fp8_sdwa v[98:99], v78 src0_sel:WORD_1
	v_cvt_pk_f32_fp8_e32 v[100:101], v79
	v_cvt_pk_f32_fp8_sdwa v[78:79], v79 src0_sel:WORD_1
	v_pk_fma_f32 v[80:81], v[198:199], v[80:81], v[84:85] op_sel:[1,0,0] op_sel_hi:[1,1,1]
	v_pk_fma_f32 v[84:85], v[198:199], v[98:99], v[88:89] op_sel:[1,0,0] op_sel_hi:[1,1,1]
	v_pk_fma_f32 v[88:89], v[198:199], v[100:101], v[92:93] op_sel:[1,0,0] op_sel_hi:[1,1,1]
	v_pk_fma_f32 v[78:79], v[198:199], v[78:79], v[82:83] op_sel:[1,0,0] op_sel_hi:[1,1,1]
	s_waitcnt vmcnt(2)
	v_cvt_pk_f32_fp8_e32 v[86:87], v72
	v_cvt_pk_f32_fp8_sdwa v[92:93], v72 src0_sel:WORD_1
	v_cvt_pk_f32_fp8_e32 v[98:99], v73
	v_cvt_pk_f32_fp8_sdwa v[72:73], v73 src0_sel:WORD_1
	v_pk_fma_f32 v[86:87], v[196:197], v[86:87], v[90:91] op_sel_hi:[0,1,1]
	v_pk_fma_f32 v[90:91], v[196:197], v[92:93], v[94:95] op_sel_hi:[0,1,1]
	v_pk_fma_f32 v[92:93], v[196:197], v[98:99], v[96:97] op_sel_hi:[0,1,1]
	v_pk_fma_f32 v[72:73], v[196:197], v[72:73], v[76:77] op_sel_hi:[0,1,1]
	v_cvt_pk_f32_fp8_e32 v[76:77], v74
	v_cvt_pk_f32_fp8_sdwa v[94:95], v74 src0_sel:WORD_1
	v_cvt_pk_f32_fp8_e32 v[96:97], v75
	v_cvt_pk_f32_fp8_sdwa v[74:75], v75 src0_sel:WORD_1
	v_pk_fma_f32 v[76:77], v[196:197], v[76:77], v[80:81] op_sel_hi:[0,1,1]
	v_pk_fma_f32 v[80:81], v[196:197], v[94:95], v[84:85] op_sel_hi:[0,1,1]
	v_pk_fma_f32 v[84:85], v[196:197], v[96:97], v[88:89] op_sel_hi:[0,1,1]
	v_pk_fma_f32 v[74:75], v[196:197], v[74:75], v[78:79] op_sel_hi:[0,1,1]
	s_waitcnt vmcnt(1)
	v_cvt_pk_f32_fp8_e32 v[82:83], v68
	v_cvt_pk_f32_fp8_sdwa v[88:89], v68 src0_sel:WORD_1
	v_cvt_pk_f32_fp8_e32 v[94:95], v69
	v_cvt_pk_f32_fp8_sdwa v[68:69], v69 src0_sel:WORD_1
	v_pk_fma_f32 v[82:83], v[196:197], v[82:83], v[86:87] op_sel:[1,0,0] op_sel_hi:[1,1,1]
	v_pk_fma_f32 v[86:87], v[196:197], v[88:89], v[90:91] op_sel:[1,0,0] op_sel_hi:[1,1,1]
	v_pk_fma_f32 v[68:69], v[196:197], v[68:69], v[72:73] op_sel:[1,0,0] op_sel_hi:[1,1,1]
	v_cvt_pk_f32_fp8_e32 v[72:73], v70
	v_pk_fma_f32 v[88:89], v[196:197], v[94:95], v[92:93] op_sel:[1,0,0] op_sel_hi:[1,1,1]
	v_cvt_pk_f32_fp8_sdwa v[90:91], v70 src0_sel:WORD_1
	v_cvt_pk_f32_fp8_e32 v[92:93], v71
	v_cvt_pk_f32_fp8_sdwa v[70:71], v71 src0_sel:WORD_1
	v_pk_fma_f32 v[72:73], v[196:197], v[72:73], v[76:77] op_sel:[1,0,0] op_sel_hi:[1,1,1]
	v_pk_fma_f32 v[76:77], v[196:197], v[90:91], v[80:81] op_sel:[1,0,0] op_sel_hi:[1,1,1]
	v_pk_fma_f32 v[80:81], v[196:197], v[92:93], v[84:85] op_sel:[1,0,0] op_sel_hi:[1,1,1]
	v_pk_fma_f32 v[70:71], v[196:197], v[70:71], v[74:75] op_sel:[1,0,0] op_sel_hi:[1,1,1]
	s_nop 1
	v_permlane32_swap_b32_e32 v82, v72
	v_permlane32_swap_b32_e32 v83, v73
	v_permlane32_swap_b32_e32 v86, v76
	v_permlane32_swap_b32_e32 v87, v77
	v_permlane32_swap_b32_e32 v88, v80
	v_permlane32_swap_b32_e32 v89, v81
	v_permlane32_swap_b32_e32 v68, v70
	v_permlane32_swap_b32_e32 v69, v71
	v_pk_add_f32 v[72:73], v[82:83], v[72:73]
	v_pk_add_f32 v[74:75], v[86:87], v[76:77]
	v_pk_add_f32 v[76:77], v[88:89], v[80:81]
	v_pk_add_f32 v[68:69], v[68:69], v[70:71]
	s_nop 1
	v_permlane16_swap_b32_e32 v72, v76
	v_permlane16_swap_b32_e32 v73, v77
	v_permlane16_swap_b32_e32 v74, v68
	v_permlane16_swap_b32_e32 v75, v69
	v_pk_add_f32 v[70:71], v[72:73], v[76:77]
	v_pk_add_f32 v[68:69], v[74:75], v[68:69]
	s_nop 0
	v_cndmask_b32_e64 v73, v71, v69, s[10:11]
	v_cndmask_b32_e64 v72, v70, v68, s[10:11]
	ds_bpermute_b32 v72, v143, v72
	ds_bpermute_b32 v73, v143, v73
	v_cndmask_b32_e64 v69, v69, v71, s[10:11]
	v_cndmask_b32_e64 v68, v68, v70, s[10:11]
	v_add_co_u32_e32 v70, vcc, 0x1000, v188
	s_waitcnt lgkmcnt(0)
	v_pk_add_f32 v[68:69], v[68:69], v[72:73]
	v_addc_co_u32_e32 v71, vcc, 0, v189, vcc
	global_store_dwordx2 v[70:71], v[68:69], off
	v_add_u32_e32 v145, 0x400, v145
	v_lshl_add_u64 v[188:189], v[188:189], 0, s[18:19]
	s_and_b64 vcc, exec, s[28:29]
	s_cbranch_vccnz .LBB0_1637
; DI void up_issue(u32x4 (&W)[16], u32 (&pj)[16], const u32* pl, const unsigned char* wbase, int grp) {
; #pragma unroll
;   for (int j = 0; j < 16; ++j) {
;     pj[j] = pl[8 * j + grp];
;     W[j] = *(const u32x4*)(wbase + (size_t)(pj[j] >> 16) * 1024);
;   }
; }
; DI void peer_up_phase(const Params& p, unsigned char* smem, int layer, u32* ctr) {
;     ...
;       for (int tl = 0; tl < 16; tl += 2) {
;         up_issue(WB, pB, pl + (tl + 1) * 128, wbase, grp);
;         __builtin_amdgcn_sched_barrier(0);
;         up_math(WA, pA, ybase + (size_t)tl * 1024, lane);
;         __builtin_amdgcn_sched_barrier(0);
.LBB0_1650:
	v_mov_b32_e32 v210, 0
	v_mov_b32_e32 v211, 0
	v_mov_b32_e32 v208, 0
	v_mov_b32_e32 v209, 0
	v_mov_b32_e32 v206, 0
	v_mov_b32_e32 v207, 0
	ds_read_u16_d16_hi v210, v145
	ds_read_u16_d16_hi v211, v145 offset:32
	ds_read_u16_d16_hi v208, v145 offset:64
	ds_read_u16_d16_hi v209, v145 offset:96
	ds_read_u16_d16_hi v206, v145 offset:128
	ds_read_u16_d16_hi v207, v145 offset:160
	ds_read_u16_d16_hi v204, v145 offset:192
	ds_read_u16_d16_hi v205, v145 offset:224
	ds_read_u16_d16_hi v202, v145 offset:256
	ds_read_u16_d16_hi v203, v145 offset:288
	ds_read_u16_d16_hi v200, v145 offset:320
	ds_read_u16_d16_hi v201, v145 offset:352
	ds_read_u16_d16_hi v198, v145 offset:384
	ds_read_u16_d16_hi v199, v145 offset:416
	ds_read_u16_d16_hi v196, v145 offset:448
	ds_read_u16_d16_hi v197, v145 offset:480
	ds_read_u16 v128, v145 offset:2
	ds_read_u16 v124, v145 offset:34
	ds_read_u16 v120, v145 offset:66
	ds_read_u16 v116, v145 offset:98
	ds_read_u16 v112, v145 offset:130
	ds_read_u16 v108, v145 offset:162
	ds_read_u16 v104, v145 offset:194
	ds_read_u16 v100, v145 offset:226
	ds_read_u16 v96, v145 offset:258
	ds_read_u16 v92, v145 offset:290
	ds_read_u16 v88, v145 offset:322
	ds_read_u16 v84, v145 offset:354
	ds_read_u16 v80, v145 offset:386
	ds_read_u16 v76, v145 offset:418
	ds_read_u16 v72, v145 offset:450
	ds_read_u16 v68, v145 offset:482
	s_waitcnt lgkmcnt(15)
	v_lshl_add_u32 v128, v128, 10, v250
	global_load_dwordx4 v[128:131], v128, s[98:99]
	s_waitcnt lgkmcnt(14)
	v_lshl_add_u32 v124, v124, 10, v250
	global_load_dwordx4 v[124:127], v124, s[98:99]
	s_waitcnt lgkmcnt(13)
	v_lshl_add_u32 v120, v120, 10, v250
	global_load_dwordx4 v[120:123], v120, s[98:99]
	s_waitcnt lgkmcnt(12)
	v_lshl_add_u32 v116, v116, 10, v250
	global_load_dwordx4 v[116:119], v116, s[98:99]
	s_waitcnt lgkmcnt(11)
	v_lshl_add_u32 v112, v112, 10, v250
	global_load_dwordx4 v[112:115], v112, s[98:99]
	s_waitcnt lgkmcnt(10)
	v_lshl_add_u32 v108, v108, 10, v250
	global_load_dwordx4 v[108:111], v108, s[98:99]
	s_waitcnt lgkmcnt(9)
	v_lshl_add_u32 v104, v104, 10, v250
	global_load_dwordx4 v[104:107], v104, s[98:99]
	s_waitcnt lgkmcnt(8)
	v_lshl_add_u32 v100, v100, 10, v250
	global_load_dwordx4 v[100:103], v100, s[98:99]
	s_waitcnt lgkmcnt(7)
	v_lshl_add_u32 v96, v96, 10, v250
	global_load_dwordx4 v[96:99], v96, s[98:99]
	s_waitcnt lgkmcnt(6)
	v_lshl_add_u32 v92, v92, 10, v250
	global_load_dwordx4 v[92:95], v92, s[98:99]
	s_waitcnt lgkmcnt(5)
	v_lshl_add_u32 v88, v88, 10, v250
	global_load_dwordx4 v[88:91], v88, s[98:99]
	s_waitcnt lgkmcnt(4)
	v_lshl_add_u32 v84, v84, 10, v250
	global_load_dwordx4 v[84:87], v84, s[98:99]
	s_waitcnt lgkmcnt(3)
	v_lshl_add_u32 v80, v80, 10, v250
	global_load_dwordx4 v[80:83], v80, s[98:99]
	s_waitcnt lgkmcnt(2)
	v_lshl_add_u32 v76, v76, 10, v250
	global_load_dwordx4 v[76:79], v76, s[98:99]
	s_waitcnt lgkmcnt(1)
	v_lshl_add_u32 v72, v72, 10, v250
	global_load_dwordx4 v[72:75], v72, s[98:99]
	s_waitcnt lgkmcnt(0)
	v_lshl_add_u32 v68, v68, 10, v250
	global_load_dwordx4 v[68:71], v68, s[98:99]
	s_waitcnt vmcnt(31)
	v_cvt_pk_f32_fp8_e32 v[216:217], v4
	v_cvt_pk_f32_fp8_sdwa v[226:227], v4 src0_sel:WORD_1
	v_cvt_pk_f32_fp8_e32 v[228:229], v5
	v_cvt_pk_f32_fp8_sdwa v[230:231], v5 src0_sel:WORD_1
	v_cvt_pk_f32_fp8_e32 v[232:233], v6
	v_cvt_pk_f32_fp8_sdwa v[234:235], v6 src0_sel:WORD_1
	v_cvt_pk_f32_fp8_e32 v[236:237], v7
	v_cvt_pk_f32_fp8_sdwa v[238:239], v7 src0_sel:WORD_1
	s_waitcnt vmcnt(30)
	v_cvt_pk_f32_fp8_e32 v[240:241], v8
	v_cvt_pk_f32_fp8_sdwa v[242:243], v8 src0_sel:WORD_1
	v_cvt_pk_f32_fp8_e32 v[244:245], v9
	v_cvt_pk_f32_fp8_sdwa v[246:247], v9 src0_sel:WORD_1
	v_pk_fma_f32 v[216:217], v[178:179], v[216:217], 0 op_sel_hi:[0,1,0]
	v_pk_fma_f32 v[226:227], v[178:179], v[226:227], 0 op_sel_hi:[0,1,0]
	v_pk_fma_f32 v[228:229], v[178:179], v[228:229], 0 op_sel_hi:[0,1,0]
	v_pk_fma_f32 v[230:231], v[178:179], v[230:231], 0 op_sel_hi:[0,1,0]
	v_pk_fma_f32 v[232:233], v[178:179], v[232:233], 0 op_sel_hi:[0,1,0]
	v_pk_fma_f32 v[234:235], v[178:179], v[234:235], 0 op_sel_hi:[0,1,0]
	v_pk_fma_f32 v[236:237], v[178:179], v[236:237], 0 op_sel_hi:[0,1,0]
	v_pk_fma_f32 v[238:239], v[178:179], v[238:239], 0 op_sel_hi:[0,1,0]
	v_pk_fma_f32 v[216:217], v[178:179], v[240:241], v[216:217] op_sel:[1,0,0] op_sel_hi:[1,1,1]
	v_cvt_pk_f32_fp8_e32 v[240:241], v10
	v_pk_fma_f32 v[226:227], v[178:179], v[242:243], v[226:227] op_sel:[1,0,0] op_sel_hi:[1,1,1]
	v_pk_fma_f32 v[228:229], v[178:179], v[244:245], v[228:229] op_sel:[1,0,0] op_sel_hi:[1,1,1]
	v_pk_fma_f32 v[230:231], v[178:179], v[246:247], v[230:231] op_sel:[1,0,0] op_sel_hi:[1,1,1]
	v_cvt_pk_f32_fp8_sdwa v[242:243], v10 src0_sel:WORD_1
	v_cvt_pk_f32_fp8_e32 v[244:245], v11
	v_cvt_pk_f32_fp8_sdwa v[246:247], v11 src0_sel:WORD_1
	v_pk_fma_f32 v[232:233], v[178:179], v[240:241], v[232:233] op_sel:[1,0,0] op_sel_hi:[1,1,1]
	s_waitcnt vmcnt(29)
	v_cvt_pk_f32_fp8_e32 v[240:241], v12
	v_pk_fma_f32 v[234:235], v[178:179], v[242:243], v[234:235] op_sel:[1,0,0] op_sel_hi:[1,1,1]
	v_pk_fma_f32 v[236:237], v[178:179], v[244:245], v[236:237] op_sel:[1,0,0] op_sel_hi:[1,1,1]
	v_pk_fma_f32 v[238:239], v[178:179], v[246:247], v[238:239] op_sel:[1,0,0] op_sel_hi:[1,1,1]
	v_cvt_pk_f32_fp8_sdwa v[242:243], v12 src0_sel:WORD_1
	v_cvt_pk_f32_fp8_e32 v[244:245], v13
	v_cvt_pk_f32_fp8_sdwa v[246:247], v13 src0_sel:WORD_1
	v_pk_fma_f32 v[216:217], v[180:181], v[240:241], v[216:217] op_sel_hi:[0,1,1]
	v_cvt_pk_f32_fp8_e32 v[240:241], v14
	v_pk_fma_f32 v[226:227], v[180:181], v[242:243], v[226:227] op_sel_hi:[0,1,1]
	v_pk_fma_f32 v[228:229], v[180:181], v[244:245], v[228:229] op_sel_hi:[0,1,1]
	v_pk_fma_f32 v[230:231], v[180:181], v[246:247], v[230:231] op_sel_hi:[0,1,1]
	v_cvt_pk_f32_fp8_sdwa v[242:243], v14 src0_sel:WORD_1
	v_cvt_pk_f32_fp8_e32 v[244:245], v15
	v_cvt_pk_f32_fp8_sdwa v[246:247], v15 src0_sel:WORD_1
	v_pk_fma_f32 v[232:233], v[180:181], v[240:241], v[232:233] op_sel_hi:[0,1,1]
	s_waitcnt vmcnt(28)
; DI void up_math(const u32x4 (&W)[16], const u32 (&pj)[16], float* __restrict__ yrow, int lane) {
;     ...
; #pragma unroll
;   for (int j = 0; j < 16; ++j) {
;     const float h = __uint_as_float(pj[j] << 16);
;     const f2 hh = {h, h};
; #pragma unroll
;     for (int d = 0; d < 4; ++d) {
;       f2 lo = __builtin_amdgcn_cvt_pk_f32_fp8((int)W[j][d], false);
;       f2 hi = __builtin_amdgcn_cvt_pk_f32_fp8((int)W[j][d], true);
;       y[2 * d] = lo * hh + y[2 * d];
;       y[2 * d + 1] = hi * hh + y[2 * d + 1];
;     }
;   }
	v_cvt_pk_f32_fp8_e32 v[240:241], v16
	v_pk_fma_f32 v[234:235], v[180:181], v[242:243], v[234:235] op_sel_hi:[0,1,1]
	v_pk_fma_f32 v[236:237], v[180:181], v[244:245], v[236:237] op_sel_hi:[0,1,1]
	v_pk_fma_f32 v[238:239], v[180:181], v[246:247], v[238:239] op_sel_hi:[0,1,1]
	v_cvt_pk_f32_fp8_sdwa v[242:243], v16 src0_sel:WORD_1
	v_cvt_pk_f32_fp8_e32 v[244:245], v17
	v_cvt_pk_f32_fp8_sdwa v[246:247], v17 src0_sel:WORD_1
	v_pk_fma_f32 v[216:217], v[180:181], v[240:241], v[216:217] op_sel:[1,0,0] op_sel_hi:[1,1,1]
	v_cvt_pk_f32_fp8_e32 v[240:241], v18
	v_pk_fma_f32 v[226:227], v[180:181], v[242:243], v[226:227] op_sel:[1,0,0] op_sel_hi:[1,1,1]
	v_pk_fma_f32 v[228:229], v[180:181], v[244:245], v[228:229] op_sel:[1,0,0] op_sel_hi:[1,1,1]
	v_pk_fma_f32 v[230:231], v[180:181], v[246:247], v[230:231] op_sel:[1,0,0] op_sel_hi:[1,1,1]
	v_cvt_pk_f32_fp8_sdwa v[242:243], v18 src0_sel:WORD_1
	v_cvt_pk_f32_fp8_e32 v[244:245], v19
	v_cvt_pk_f32_fp8_sdwa v[246:247], v19 src0_sel:WORD_1
	v_pk_fma_f32 v[232:233], v[180:181], v[240:241], v[232:233] op_sel:[1,0,0] op_sel_hi:[1,1,1]
	s_waitcnt vmcnt(27)
	v_cvt_pk_f32_fp8_e32 v[240:241], v20
	v_pk_fma_f32 v[234:235], v[180:181], v[242:243], v[234:235] op_sel:[1,0,0] op_sel_hi:[1,1,1]
	v_pk_fma_f32 v[236:237], v[180:181], v[244:245], v[236:237] op_sel:[1,0,0] op_sel_hi:[1,1,1]
	v_pk_fma_f32 v[238:239], v[180:181], v[246:247], v[238:239] op_sel:[1,0,0] op_sel_hi:[1,1,1]
	v_cvt_pk_f32_fp8_sdwa v[242:243], v20 src0_sel:WORD_1
	v_cvt_pk_f32_fp8_e32 v[244:245], v21
	v_cvt_pk_f32_fp8_sdwa v[246:247], v21 src0_sel:WORD_1
	v_pk_fma_f32 v[216:217], v[182:183], v[240:241], v[216:217] op_sel_hi:[0,1,1]
	v_cvt_pk_f32_fp8_e32 v[240:241], v22
	v_pk_fma_f32 v[226:227], v[182:183], v[242:243], v[226:227] op_sel_hi:[0,1,1]
	v_pk_fma_f32 v[228:229], v[182:183], v[244:245], v[228:229] op_sel_hi:[0,1,1]
	v_pk_fma_f32 v[230:231], v[182:183], v[246:247], v[230:231] op_sel_hi:[0,1,1]
	v_cvt_pk_f32_fp8_sdwa v[242:243], v22 src0_sel:WORD_1
	v_cvt_pk_f32_fp8_e32 v[244:245], v23
	v_cvt_pk_f32_fp8_sdwa v[246:247], v23 src0_sel:WORD_1
	v_pk_fma_f32 v[232:233], v[182:183], v[240:241], v[232:233] op_sel_hi:[0,1,1]
	s_waitcnt vmcnt(26)
	v_cvt_pk_f32_fp8_e32 v[240:241], v24
	v_pk_fma_f32 v[234:235], v[182:183], v[242:243], v[234:235] op_sel_hi:[0,1,1]
	v_pk_fma_f32 v[236:237], v[182:183], v[244:245], v[236:237] op_sel_hi:[0,1,1]
	v_pk_fma_f32 v[238:239], v[182:183], v[246:247], v[238:239] op_sel_hi:[0,1,1]
	v_cvt_pk_f32_fp8_sdwa v[242:243], v24 src0_sel:WORD_1
	v_cvt_pk_f32_fp8_e32 v[244:245], v25
	v_cvt_pk_f32_fp8_sdwa v[246:247], v25 src0_sel:WORD_1
	v_pk_fma_f32 v[216:217], v[182:183], v[240:241], v[216:217] op_sel:[1,0,0] op_sel_hi:[1,1,1]
	v_cvt_pk_f32_fp8_e32 v[240:241], v26
	v_pk_fma_f32 v[226:227], v[182:183], v[242:243], v[226:227] op_sel:[1,0,0] op_sel_hi:[1,1,1]
	v_pk_fma_f32 v[228:229], v[182:183], v[244:245], v[228:229] op_sel:[1,0,0] op_sel_hi:[1,1,1]
	v_pk_fma_f32 v[230:231], v[182:183], v[246:247], v[230:231] op_sel:[1,0,0] op_sel_hi:[1,1,1]
	v_cvt_pk_f32_fp8_sdwa v[242:243], v26 src0_sel:WORD_1
	v_cvt_pk_f32_fp8_e32 v[244:245], v27
	v_cvt_pk_f32_fp8_sdwa v[246:247], v27 src0_sel:WORD_1
	v_pk_fma_f32 v[232:233], v[182:183], v[240:241], v[232:233] op_sel:[1,0,0] op_sel_hi:[1,1,1]
	s_waitcnt vmcnt(25)
	v_cvt_pk_f32_fp8_e32 v[240:241], v28
	v_pk_fma_f32 v[234:235], v[182:183], v[242:243], v[234:235] op_sel:[1,0,0] op_sel_hi:[1,1,1]
	v_pk_fma_f32 v[236:237], v[182:183], v[244:245], v[236:237] op_sel:[1,0,0] op_sel_hi:[1,1,1]
	v_pk_fma_f32 v[238:239], v[182:183], v[246:247], v[238:239] op_sel:[1,0,0] op_sel_hi:[1,1,1]
	v_cvt_pk_f32_fp8_sdwa v[242:243], v28 src0_sel:WORD_1
	v_cvt_pk_f32_fp8_e32 v[244:245], v29
	v_cvt_pk_f32_fp8_sdwa v[246:247], v29 src0_sel:WORD_1
	v_pk_fma_f32 v[216:217], v[184:185], v[240:241], v[216:217] op_sel_hi:[0,1,1]
	v_cvt_pk_f32_fp8_e32 v[240:241], v30
	v_pk_fma_f32 v[226:227], v[184:185], v[242:243], v[226:227] op_sel_hi:[0,1,1]
	v_pk_fma_f32 v[228:229], v[184:185], v[244:245], v[228:229] op_sel_hi:[0,1,1]
	v_pk_fma_f32 v[230:231], v[184:185], v[246:247], v[230:231] op_sel_hi:[0,1,1]
	v_cvt_pk_f32_fp8_sdwa v[242:243], v30 src0_sel:WORD_1
	v_cvt_pk_f32_fp8_e32 v[244:245], v31
	v_cvt_pk_f32_fp8_sdwa v[246:247], v31 src0_sel:WORD_1
	v_pk_fma_f32 v[232:233], v[184:185], v[240:241], v[232:233] op_sel_hi:[0,1,1]
	s_waitcnt vmcnt(24)
	v_cvt_pk_f32_fp8_e32 v[240:241], v32
	v_pk_fma_f32 v[234:235], v[184:185], v[242:243], v[234:235] op_sel_hi:[0,1,1]
	v_pk_fma_f32 v[236:237], v[184:185], v[244:245], v[236:237] op_sel_hi:[0,1,1]
	v_pk_fma_f32 v[238:239], v[184:185], v[246:247], v[238:239] op_sel_hi:[0,1,1]
	v_cvt_pk_f32_fp8_sdwa v[242:243], v32 src0_sel:WORD_1
	v_cvt_pk_f32_fp8_e32 v[244:245], v33
	v_cvt_pk_f32_fp8_sdwa v[246:247], v33 src0_sel:WORD_1
	v_pk_fma_f32 v[216:217], v[184:185], v[240:241], v[216:217] op_sel:[1,0,0] op_sel_hi:[1,1,1]
	v_cvt_pk_f32_fp8_e32 v[240:241], v34
	v_pk_fma_f32 v[226:227], v[184:185], v[242:243], v[226:227] op_sel:[1,0,0] op_sel_hi:[1,1,1]
	v_pk_fma_f32 v[228:229], v[184:185], v[244:245], v[228:229] op_sel:[1,0,0] op_sel_hi:[1,1,1]
	v_pk_fma_f32 v[230:231], v[184:185], v[246:247], v[230:231] op_sel:[1,0,0] op_sel_hi:[1,1,1]
	v_cvt_pk_f32_fp8_sdwa v[242:243], v34 src0_sel:WORD_1
	v_cvt_pk_f32_fp8_e32 v[244:245], v35
	v_cvt_pk_f32_fp8_sdwa v[246:247], v35 src0_sel:WORD_1
	v_pk_fma_f32 v[232:233], v[184:185], v[240:241], v[232:233] op_sel:[1,0,0] op_sel_hi:[1,1,1]
	s_waitcnt vmcnt(23)
; DI void up_math(const u32x4 (&W)[16], const u32 (&pj)[16], float* __restrict__ yrow, int lane) {
;     ...
; #pragma unroll
;   for (int j = 0; j < 16; ++j) {
;     const float h = __uint_as_float(pj[j] << 16);
;     const f2 hh = {h, h};
; #pragma unroll
;     for (int d = 0; d < 4; ++d) {
;       f2 lo = __builtin_amdgcn_cvt_pk_f32_fp8((int)W[j][d], false);
;       f2 hi = __builtin_amdgcn_cvt_pk_f32_fp8((int)W[j][d], true);
;       y[2 * d] = lo * hh + y[2 * d];
;       y[2 * d + 1] = hi * hh + y[2 * d + 1];
;     }
;   }
	v_cvt_pk_f32_fp8_e32 v[240:241], v36
	v_pk_fma_f32 v[234:235], v[184:185], v[242:243], v[234:235] op_sel:[1,0,0] op_sel_hi:[1,1,1]
	v_pk_fma_f32 v[236:237], v[184:185], v[244:245], v[236:237] op_sel:[1,0,0] op_sel_hi:[1,1,1]
	v_pk_fma_f32 v[238:239], v[184:185], v[246:247], v[238:239] op_sel:[1,0,0] op_sel_hi:[1,1,1]
	v_cvt_pk_f32_fp8_sdwa v[242:243], v36 src0_sel:WORD_1
	v_cvt_pk_f32_fp8_e32 v[244:245], v37
	v_cvt_pk_f32_fp8_sdwa v[246:247], v37 src0_sel:WORD_1
	v_pk_fma_f32 v[216:217], v[186:187], v[240:241], v[216:217] op_sel_hi:[0,1,1]
	v_cvt_pk_f32_fp8_e32 v[240:241], v38
	v_pk_fma_f32 v[226:227], v[186:187], v[242:243], v[226:227] op_sel_hi:[0,1,1]
	v_pk_fma_f32 v[228:229], v[186:187], v[244:245], v[228:229] op_sel_hi:[0,1,1]
	v_pk_fma_f32 v[230:231], v[186:187], v[246:247], v[230:231] op_sel_hi:[0,1,1]
	v_cvt_pk_f32_fp8_sdwa v[242:243], v38 src0_sel:WORD_1
	v_cvt_pk_f32_fp8_e32 v[244:245], v39
	v_cvt_pk_f32_fp8_sdwa v[246:247], v39 src0_sel:WORD_1
	v_pk_fma_f32 v[232:233], v[186:187], v[240:241], v[232:233] op_sel_hi:[0,1,1]
	s_waitcnt vmcnt(22)
	v_cvt_pk_f32_fp8_e32 v[240:241], v40
	v_pk_fma_f32 v[234:235], v[186:187], v[242:243], v[234:235] op_sel_hi:[0,1,1]
	v_pk_fma_f32 v[236:237], v[186:187], v[244:245], v[236:237] op_sel_hi:[0,1,1]
	v_pk_fma_f32 v[238:239], v[186:187], v[246:247], v[238:239] op_sel_hi:[0,1,1]
	v_cvt_pk_f32_fp8_sdwa v[242:243], v40 src0_sel:WORD_1
	v_cvt_pk_f32_fp8_e32 v[244:245], v41
	v_cvt_pk_f32_fp8_sdwa v[246:247], v41 src0_sel:WORD_1
	v_pk_fma_f32 v[216:217], v[186:187], v[240:241], v[216:217] op_sel:[1,0,0] op_sel_hi:[1,1,1]
	v_cvt_pk_f32_fp8_e32 v[240:241], v42
	v_pk_fma_f32 v[226:227], v[186:187], v[242:243], v[226:227] op_sel:[1,0,0] op_sel_hi:[1,1,1]
	v_pk_fma_f32 v[228:229], v[186:187], v[244:245], v[228:229] op_sel:[1,0,0] op_sel_hi:[1,1,1]
	v_pk_fma_f32 v[230:231], v[186:187], v[246:247], v[230:231] op_sel:[1,0,0] op_sel_hi:[1,1,1]
	v_cvt_pk_f32_fp8_sdwa v[242:243], v42 src0_sel:WORD_1
	v_cvt_pk_f32_fp8_e32 v[244:245], v43
	v_cvt_pk_f32_fp8_sdwa v[246:247], v43 src0_sel:WORD_1
	v_pk_fma_f32 v[232:233], v[186:187], v[240:241], v[232:233] op_sel:[1,0,0] op_sel_hi:[1,1,1]
	s_waitcnt vmcnt(21)
	v_cvt_pk_f32_fp8_e32 v[240:241], v44
	v_pk_fma_f32 v[234:235], v[186:187], v[242:243], v[234:235] op_sel:[1,0,0] op_sel_hi:[1,1,1]
	v_pk_fma_f32 v[236:237], v[186:187], v[244:245], v[236:237] op_sel:[1,0,0] op_sel_hi:[1,1,1]
	v_pk_fma_f32 v[238:239], v[186:187], v[246:247], v[238:239] op_sel:[1,0,0] op_sel_hi:[1,1,1]
	v_cvt_pk_f32_fp8_sdwa v[242:243], v44 src0_sel:WORD_1
	v_cvt_pk_f32_fp8_e32 v[244:245], v45
	v_cvt_pk_f32_fp8_sdwa v[246:247], v45 src0_sel:WORD_1
	v_pk_fma_f32 v[216:217], v[190:191], v[240:241], v[216:217] op_sel_hi:[0,1,1]
	v_cvt_pk_f32_fp8_e32 v[240:241], v46
	v_pk_fma_f32 v[226:227], v[190:191], v[242:243], v[226:227] op_sel_hi:[0,1,1]
	v_pk_fma_f32 v[228:229], v[190:191], v[244:245], v[228:229] op_sel_hi:[0,1,1]
	v_pk_fma_f32 v[230:231], v[190:191], v[246:247], v[230:231] op_sel_hi:[0,1,1]
	v_cvt_pk_f32_fp8_sdwa v[242:243], v46 src0_sel:WORD_1
	v_cvt_pk_f32_fp8_e32 v[244:245], v47
	v_cvt_pk_f32_fp8_sdwa v[246:247], v47 src0_sel:WORD_1
	v_pk_fma_f32 v[232:233], v[190:191], v[240:241], v[232:233] op_sel_hi:[0,1,1]
	s_waitcnt vmcnt(20)
	v_cvt_pk_f32_fp8_e32 v[240:241], v48
	v_pk_fma_f32 v[234:235], v[190:191], v[242:243], v[234:235] op_sel_hi:[0,1,1]
	v_pk_fma_f32 v[236:237], v[190:191], v[244:245], v[236:237] op_sel_hi:[0,1,1]
	v_pk_fma_f32 v[238:239], v[190:191], v[246:247], v[238:239] op_sel_hi:[0,1,1]
	v_cvt_pk_f32_fp8_sdwa v[242:243], v48 src0_sel:WORD_1
	v_cvt_pk_f32_fp8_e32 v[244:245], v49
	v_cvt_pk_f32_fp8_sdwa v[246:247], v49 src0_sel:WORD_1
	v_pk_fma_f32 v[216:217], v[190:191], v[240:241], v[216:217] op_sel:[1,0,0] op_sel_hi:[1,1,1]
	v_cvt_pk_f32_fp8_e32 v[240:241], v50
	v_pk_fma_f32 v[226:227], v[190:191], v[242:243], v[226:227] op_sel:[1,0,0] op_sel_hi:[1,1,1]
	v_pk_fma_f32 v[228:229], v[190:191], v[244:245], v[228:229] op_sel:[1,0,0] op_sel_hi:[1,1,1]
	v_pk_fma_f32 v[230:231], v[190:191], v[246:247], v[230:231] op_sel:[1,0,0] op_sel_hi:[1,1,1]
	v_cvt_pk_f32_fp8_sdwa v[242:243], v50 src0_sel:WORD_1
	v_cvt_pk_f32_fp8_e32 v[244:245], v51
	v_cvt_pk_f32_fp8_sdwa v[246:247], v51 src0_sel:WORD_1
	v_pk_fma_f32 v[232:233], v[190:191], v[240:241], v[232:233] op_sel:[1,0,0] op_sel_hi:[1,1,1]
	s_waitcnt vmcnt(19)
	v_cvt_pk_f32_fp8_e32 v[240:241], v52
	v_pk_fma_f32 v[234:235], v[190:191], v[242:243], v[234:235] op_sel:[1,0,0] op_sel_hi:[1,1,1]
	v_pk_fma_f32 v[236:237], v[190:191], v[244:245], v[236:237] op_sel:[1,0,0] op_sel_hi:[1,1,1]
	v_pk_fma_f32 v[238:239], v[190:191], v[246:247], v[238:239] op_sel:[1,0,0] op_sel_hi:[1,1,1]
	v_cvt_pk_f32_fp8_sdwa v[242:243], v52 src0_sel:WORD_1
	v_cvt_pk_f32_fp8_e32 v[244:245], v53
	v_cvt_pk_f32_fp8_sdwa v[246:247], v53 src0_sel:WORD_1
	v_pk_fma_f32 v[216:217], v[192:193], v[240:241], v[216:217] op_sel_hi:[0,1,1]
	v_cvt_pk_f32_fp8_e32 v[240:241], v54
	v_pk_fma_f32 v[226:227], v[192:193], v[242:243], v[226:227] op_sel_hi:[0,1,1]
	v_pk_fma_f32 v[228:229], v[192:193], v[244:245], v[228:229] op_sel_hi:[0,1,1]
	v_pk_fma_f32 v[230:231], v[192:193], v[246:247], v[230:231] op_sel_hi:[0,1,1]
	v_cvt_pk_f32_fp8_sdwa v[242:243], v54 src0_sel:WORD_1
	v_cvt_pk_f32_fp8_e32 v[244:245], v55
	v_cvt_pk_f32_fp8_sdwa v[246:247], v55 src0_sel:WORD_1
	v_pk_fma_f32 v[232:233], v[192:193], v[240:241], v[232:233] op_sel_hi:[0,1,1]
	s_waitcnt vmcnt(18)
; DI void up_math(const u32x4 (&W)[16], const u32 (&pj)[16], float* __restrict__ yrow, int lane) {
;     ...
; #pragma unroll
;   for (int j = 0; j < 16; ++j) {
;     const float h = __uint_as_float(pj[j] << 16);
;     const f2 hh = {h, h};
; #pragma unroll
;     for (int d = 0; d < 4; ++d) {
;       f2 lo = __builtin_amdgcn_cvt_pk_f32_fp8((int)W[j][d], false);
;       f2 hi = __builtin_amdgcn_cvt_pk_f32_fp8((int)W[j][d], true);
;       y[2 * d] = lo * hh + y[2 * d];
;       y[2 * d + 1] = hi * hh + y[2 * d + 1];
;     }
;   }
;   const bool b5 = lane & 32, b4 = lane & 16, b3 = lane & 8;
;   f2 q4[4];
; #pragma unroll
;   for (int i = 0; i < 4; ++i) {
;     f2 snd = b5 ? y[i] : y[i + 4]; f2 kp = b5 ? y[i + 4] : y[i];
;     q4[i] = f2{kp.x + __shfl_xor(snd.x, 32), kp.y + __shfl_xor(snd.y, 32)};
;   }
;   f2 r2[2];
; #pragma unroll
;   for (int i = 0; i < 2; ++i) {
;     f2 snd = b4 ? q4[i] : q4[i + 2]; f2 kp = b4 ? q4[i + 2] : q4[i];
;     r2[i] = f2{kp.x + __shfl_xor(snd.x, 16), kp.y + __shfl_xor(snd.y, 16)};
;   }
;   f2 a;
;   { f2 snd = b3 ? r2[0] : r2[1]; f2 kp = b3 ? r2[1] : r2[0]; a = f2{kp.x + __shfl_xor(snd.x, 8), kp.y + __shfl_xor(snd.y, 8)}; }
;   const int ci = (b5 ? 4 : 0) + (b4 ? 2 : 0) + (b3 ? 1 : 0);
;   *(float2*)(yrow + (lane & 7) * 16 + 2 * ci) = make_float2(a.x, a.y);
; }
; DI void peer_up_phase(const Params& p, unsigned char* smem, int layer, u32* ctr) {
;     ...
;       for (int tl = 0; tl < 16; tl += 2) {
;         up_issue(WB, pB, pl + (tl + 1) * 128, wbase, grp);
;         __builtin_amdgcn_sched_barrier(0);
;         up_math(WA, pA, ybase + (size_t)tl * 1024, lane);
;         __builtin_amdgcn_sched_barrier(0);
;         if (tl + 2 < 16) up_issue(WA, pA, pl + (tl + 2) * 128, wbase, grp);
;         __builtin_amdgcn_sched_barrier(0);
;         up_math(WB, pB, ybase + (size_t)(tl + 1) * 1024, lane);
;         __builtin_amdgcn_sched_barrier(0);
;       }
	v_cvt_pk_f32_fp8_e32 v[240:241], v56
	v_pk_fma_f32 v[234:235], v[192:193], v[242:243], v[234:235] op_sel_hi:[0,1,1]
	v_pk_fma_f32 v[236:237], v[192:193], v[244:245], v[236:237] op_sel_hi:[0,1,1]
	v_pk_fma_f32 v[238:239], v[192:193], v[246:247], v[238:239] op_sel_hi:[0,1,1]
	v_cvt_pk_f32_fp8_sdwa v[242:243], v56 src0_sel:WORD_1
	v_cvt_pk_f32_fp8_e32 v[244:245], v57
	v_cvt_pk_f32_fp8_sdwa v[246:247], v57 src0_sel:WORD_1
	v_pk_fma_f32 v[216:217], v[192:193], v[240:241], v[216:217] op_sel:[1,0,0] op_sel_hi:[1,1,1]
	v_cvt_pk_f32_fp8_e32 v[240:241], v58
	v_pk_fma_f32 v[226:227], v[192:193], v[242:243], v[226:227] op_sel:[1,0,0] op_sel_hi:[1,1,1]
	v_pk_fma_f32 v[228:229], v[192:193], v[244:245], v[228:229] op_sel:[1,0,0] op_sel_hi:[1,1,1]
	v_pk_fma_f32 v[230:231], v[192:193], v[246:247], v[230:231] op_sel:[1,0,0] op_sel_hi:[1,1,1]
	v_cvt_pk_f32_fp8_sdwa v[242:243], v58 src0_sel:WORD_1
	v_cvt_pk_f32_fp8_e32 v[244:245], v59
	v_cvt_pk_f32_fp8_sdwa v[246:247], v59 src0_sel:WORD_1
	v_pk_fma_f32 v[232:233], v[192:193], v[240:241], v[232:233] op_sel:[1,0,0] op_sel_hi:[1,1,1]
	s_waitcnt vmcnt(17)
	v_cvt_pk_f32_fp8_e32 v[240:241], v60
	v_pk_fma_f32 v[234:235], v[192:193], v[242:243], v[234:235] op_sel:[1,0,0] op_sel_hi:[1,1,1]
	v_pk_fma_f32 v[236:237], v[192:193], v[244:245], v[236:237] op_sel:[1,0,0] op_sel_hi:[1,1,1]
	v_pk_fma_f32 v[238:239], v[192:193], v[246:247], v[238:239] op_sel:[1,0,0] op_sel_hi:[1,1,1]
	v_cvt_pk_f32_fp8_sdwa v[242:243], v60 src0_sel:WORD_1
	v_cvt_pk_f32_fp8_e32 v[244:245], v61
	v_cvt_pk_f32_fp8_sdwa v[246:247], v61 src0_sel:WORD_1
	v_pk_fma_f32 v[216:217], v[194:195], v[240:241], v[216:217] op_sel_hi:[0,1,1]
	v_cvt_pk_f32_fp8_e32 v[240:241], v62
	v_pk_fma_f32 v[226:227], v[194:195], v[242:243], v[226:227] op_sel_hi:[0,1,1]
	v_pk_fma_f32 v[228:229], v[194:195], v[244:245], v[228:229] op_sel_hi:[0,1,1]
	v_pk_fma_f32 v[230:231], v[194:195], v[246:247], v[230:231] op_sel_hi:[0,1,1]
	v_cvt_pk_f32_fp8_sdwa v[242:243], v62 src0_sel:WORD_1
	v_cvt_pk_f32_fp8_e32 v[244:245], v63
	v_cvt_pk_f32_fp8_sdwa v[246:247], v63 src0_sel:WORD_1
	v_pk_fma_f32 v[232:233], v[194:195], v[240:241], v[232:233] op_sel_hi:[0,1,1]
	s_waitcnt vmcnt(16)
	v_cvt_pk_f32_fp8_e32 v[240:241], v64
	v_pk_fma_f32 v[234:235], v[194:195], v[242:243], v[234:235] op_sel_hi:[0,1,1]
	v_pk_fma_f32 v[236:237], v[194:195], v[244:245], v[236:237] op_sel_hi:[0,1,1]
	v_pk_fma_f32 v[238:239], v[194:195], v[246:247], v[238:239] op_sel_hi:[0,1,1]
	v_cvt_pk_f32_fp8_sdwa v[242:243], v64 src0_sel:WORD_1
	v_cvt_pk_f32_fp8_e32 v[244:245], v65
	v_cvt_pk_f32_fp8_sdwa v[246:247], v65 src0_sel:WORD_1
	v_pk_fma_f32 v[216:217], v[194:195], v[240:241], v[216:217] op_sel:[1,0,0] op_sel_hi:[1,1,1]
	v_cvt_pk_f32_fp8_e32 v[240:241], v66
	v_pk_fma_f32 v[226:227], v[194:195], v[242:243], v[226:227] op_sel:[1,0,0] op_sel_hi:[1,1,1]
	v_pk_fma_f32 v[228:229], v[194:195], v[244:245], v[228:229] op_sel:[1,0,0] op_sel_hi:[1,1,1]
	v_pk_fma_f32 v[230:231], v[194:195], v[246:247], v[230:231] op_sel:[1,0,0] op_sel_hi:[1,1,1]
	v_cvt_pk_f32_fp8_sdwa v[242:243], v66 src0_sel:WORD_1
	v_cvt_pk_f32_fp8_e32 v[244:245], v67
	v_cvt_pk_f32_fp8_sdwa v[246:247], v67 src0_sel:WORD_1
	v_pk_fma_f32 v[232:233], v[194:195], v[240:241], v[232:233] op_sel:[1,0,0] op_sel_hi:[1,1,1]
	v_pk_fma_f32 v[234:235], v[194:195], v[242:243], v[234:235] op_sel:[1,0,0] op_sel_hi:[1,1,1]
	v_pk_fma_f32 v[236:237], v[194:195], v[244:245], v[236:237] op_sel:[1,0,0] op_sel_hi:[1,1,1]
	v_pk_fma_f32 v[238:239], v[194:195], v[246:247], v[238:239] op_sel:[1,0,0] op_sel_hi:[1,1,1]
	s_nop 1
	v_permlane32_swap_b32_e32 v216, v232
	v_permlane32_swap_b32_e32 v217, v233
	v_permlane32_swap_b32_e32 v228, v236
	v_permlane32_swap_b32_e32 v229, v237
	v_permlane32_swap_b32_e32 v226, v234
	v_permlane32_swap_b32_e32 v227, v235
	v_permlane32_swap_b32_e32 v230, v238
	v_permlane32_swap_b32_e32 v231, v239
	v_pk_add_f32 v[216:217], v[216:217], v[232:233]
	v_pk_add_f32 v[228:229], v[228:229], v[236:237]
	v_pk_add_f32 v[226:227], v[226:227], v[234:235]
	v_pk_add_f32 v[230:231], v[230:231], v[238:239]
	s_nop 1
	v_permlane16_swap_b32_e32 v216, v228
	v_permlane16_swap_b32_e32 v217, v229
	v_permlane16_swap_b32_e32 v226, v230
	v_permlane16_swap_b32_e32 v227, v231
	v_pk_add_f32 v[216:217], v[216:217], v[228:229]
	v_pk_add_f32 v[226:227], v[226:227], v[230:231]
	s_nop 0
	v_cndmask_b32_e64 v132, v217, v227, s[10:11]
	v_cndmask_b32_e64 v147, v216, v226, s[10:11]
	ds_bpermute_b32 v228, v143, v147
	ds_bpermute_b32 v229, v143, v132
	v_cndmask_b32_e64 v217, v227, v217, s[10:11]
	v_cndmask_b32_e64 v216, v226, v216, s[10:11]
	s_waitcnt lgkmcnt(0)
	v_pk_add_f32 v[216:217], v[216:217], v[228:229]
	global_store_dwordx2 v[188:189], v[216:217], off
	s_cmp_gt_u32 s36, 13
	s_cselect_b64 s[28:29], -1, 0
	s_and_b64 vcc, exec, s[28:29]
	s_cbranch_vccnz .LBB0_1649
; DI void up_issue(u32x4 (&W)[16], u32 (&pj)[16], const u32* pl, const unsigned char* wbase, int grp) {
; #pragma unroll
;   for (int j = 0; j < 16; ++j) {
;     pj[j] = pl[8 * j + grp];
;     W[j] = *(const u32x4*)(wbase + (size_t)(pj[j] >> 16) * 1024);
;   }
; }
; DI void peer_up_phase(const Params& p, unsigned char* smem, int layer, u32* ctr) {
;     ...
;         if (tl + 2 < 16) up_issue(WA, pA, pl + (tl + 2) * 128, wbase, grp);
	ds_read_u16_d16_hi v178, v145 offset:512
	ds_read_u16_d16_hi v179, v145 offset:544
	ds_read_u16_d16_hi v180, v145 offset:576
	ds_read_u16_d16_hi v181, v145 offset:608
	ds_read_u16_d16_hi v182, v145 offset:640
	ds_read_u16_d16_hi v183, v145 offset:672
	ds_read_u16_d16_hi v184, v145 offset:704
	ds_read_u16_d16_hi v185, v145 offset:736
	ds_read_u16_d16_hi v186, v145 offset:768
	ds_read_u16_d16_hi v187, v145 offset:800
	ds_read_u16_d16_hi v190, v145 offset:832
	ds_read_u16_d16_hi v191, v145 offset:864
	ds_read_u16_d16_hi v192, v145 offset:896
	ds_read_u16_d16_hi v193, v145 offset:928
	ds_read_u16_d16_hi v194, v145 offset:960
	ds_read_u16_d16_hi v195, v145 offset:992
	ds_read_u16 v4, v145 offset:514
	ds_read_u16 v8, v145 offset:546
	ds_read_u16 v12, v145 offset:578
	ds_read_u16 v16, v145 offset:610
	ds_read_u16 v20, v145 offset:642
	ds_read_u16 v24, v145 offset:674
	ds_read_u16 v28, v145 offset:706
	ds_read_u16 v32, v145 offset:738
	ds_read_u16 v36, v145 offset:770
	ds_read_u16 v40, v145 offset:802
	ds_read_u16 v44, v145 offset:834
	ds_read_u16 v48, v145 offset:866
	ds_read_u16 v52, v145 offset:898
	ds_read_u16 v56, v145 offset:930
	ds_read_u16 v60, v145 offset:962
	ds_read_u16 v64, v145 offset:994
	s_waitcnt lgkmcnt(15)
	v_lshl_add_u32 v4, v4, 10, v250
	global_load_dwordx4 v[4:7], v4, s[98:99]
	s_waitcnt lgkmcnt(14)
	v_lshl_add_u32 v8, v8, 10, v250
	global_load_dwordx4 v[8:11], v8, s[98:99]
	s_waitcnt lgkmcnt(13)
	v_lshl_add_u32 v12, v12, 10, v250
	global_load_dwordx4 v[12:15], v12, s[98:99]
	s_waitcnt lgkmcnt(12)
	v_lshl_add_u32 v16, v16, 10, v250
	global_load_dwordx4 v[16:19], v16, s[98:99]
	s_waitcnt lgkmcnt(11)
	v_lshl_add_u32 v20, v20, 10, v250
	global_load_dwordx4 v[20:23], v20, s[98:99]
	s_waitcnt lgkmcnt(10)
	v_lshl_add_u32 v24, v24, 10, v250
	global_load_dwordx4 v[24:27], v24, s[98:99]
	s_waitcnt lgkmcnt(9)
	v_lshl_add_u32 v28, v28, 10, v250
	global_load_dwordx4 v[28:31], v28, s[98:99]
	s_waitcnt lgkmcnt(8)
	v_lshl_add_u32 v32, v32, 10, v250
	global_load_dwordx4 v[32:35], v32, s[98:99]
	s_waitcnt lgkmcnt(7)
	v_lshl_add_u32 v36, v36, 10, v250
	global_load_dwordx4 v[36:39], v36, s[98:99]
	s_waitcnt lgkmcnt(6)
	v_lshl_add_u32 v40, v40, 10, v250
	global_load_dwordx4 v[40:43], v40, s[98:99]
	s_waitcnt lgkmcnt(5)
	v_lshl_add_u32 v44, v44, 10, v250
	global_load_dwordx4 v[44:47], v44, s[98:99]
	s_waitcnt lgkmcnt(4)
	v_lshl_add_u32 v48, v48, 10, v250
	global_load_dwordx4 v[48:51], v48, s[98:99]
	s_waitcnt lgkmcnt(3)
	v_lshl_add_u32 v52, v52, 10, v250
	global_load_dwordx4 v[52:55], v52, s[98:99]
	s_waitcnt lgkmcnt(2)
	v_lshl_add_u32 v56, v56, 10, v250
	global_load_dwordx4 v[56:59], v56, s[98:99]
	s_waitcnt lgkmcnt(1)
	v_lshl_add_u32 v60, v60, 10, v250
	global_load_dwordx4 v[60:63], v60, s[98:99]
	s_waitcnt lgkmcnt(0)
	v_lshl_add_u32 v64, v64, 10, v250
	global_load_dwordx4 v[64:67], v64, s[98:99]
	s_branch .LBB0_1649
